# V^T stored with middle key-quads swapped per 16 keys (PROJ + up-projection epilogues) so attention PV reads one conflict-free ds_read_b128 per fragment
# speedup vs baseline: 1.0544x; 1.0140x over previous
; DI void phase_proj(const P& p, int l, char* smem) {
;     ...
;       } else if (nb < 1440) {
;         const int kh = (n - 1312) >> 6, d = (n - 1312) & 63;
;         const int s = srb - b * SA;
;         h16* vt = VgT + ((size_t)(b * 2 + kh) * 64 + d) * SA + s;
; #pragma unroll
;         for (int g = 0; g < 4; ++g) {
;           h16x4 o; o.x = (h16)v[4 * g]; o.y = (h16)v[4 * g + 1]; o.z = (h16)v[4 * g + 2]; o.w = (h16)v[4 * g + 3];
;           *(h16x4*)(vt + 8 * g) = o;
;         }
.LBB0_843:
	s_andn2_saveexec_b64 s[12:13], s[12:13]
	s_cbranch_execz .LBB0_845
	v_add_u32_e32 v0, 0xfffffae0, v130
	v_lshrrev_b32_e32 v137, 6, v0
	v_lshl_add_u32 v138, v131, 1, v137
	v_ashrrev_i32_e32 v139, 31, v138
	s_movk_i32 s3, 0xef00
	v_lshlrev_b64 v[138:139], 6, v[138:139]
	v_mad_u64_u32 v[132:133], s[14:15], v131, s3, v[132:133]
	v_and_or_b32 v0, v0, 63, v138
	v_mov_b64_e32 v[140:141], s[60:61]
	s_movk_i32 s3, 0x2200
	v_mad_u64_u32 v[140:141], s[14:15], v0, s3, v[140:141]
	v_mad_i32_i24 v141, v139, s3, v141
	v_ashrrev_i32_e32 v133, 31, v132
	v_lshl_add_u64 v[132:133], v[132:133], 1, v[140:141]
	v_bfe_u32 v140, v203, 5, 1
	v_lshlrev_b32_e32 v140, 3, v140
	v_mov_b32_e32 v141, 0
	v_lshl_add_u64 v[132:133], v[132:133], 0, v[140:141]
	v_cvt_pk_f16_f32 v139, v116, v117
	v_cvt_pk_f16_f32 v138, v114, v115
	global_store_dwordx2 v[132:133], v[138:139], off
	v_cvt_pk_f16_f32 v139, v120, v121
	v_cvt_pk_f16_f32 v138, v118, v119
	global_store_dwordx2 v[132:133], v[138:139], off offset:8
	v_cvt_pk_f16_f32 v139, v124, v125
	v_cvt_pk_f16_f32 v138, v122, v123
	global_store_dwordx2 v[132:133], v[138:139], off offset:32
	v_cvt_pk_f16_f32 v139, v128, v129
	v_cvt_pk_f16_f32 v138, v126, v127
	global_store_dwordx2 v[132:133], v[138:139], off offset:40

; DI void phase_proj(const P& p, int l, char* smem) {
;     ...
;       } else if (nb < 1440) {
;         const int kh = (n - 1312) >> 6, d = (n - 1312) & 63;
;         const int s = srb - b * SA;
;         h16* vt = VgT + ((size_t)(b * 2 + kh) * 64 + d) * SA + s;
; #pragma unroll
;         for (int g = 0; g < 4; ++g) {
;           h16x4 o; o.x = (h16)v[4 * g]; o.y = (h16)v[4 * g + 1]; o.z = (h16)v[4 * g + 2]; o.w = (h16)v[4 * g + 3];
;           *(h16x4*)(vt + 8 * g) = o;
;         }
.LBB0_1000:
	s_andn2_saveexec_b64 s[12:13], s[12:13]
	s_cbranch_execz .LBB0_1002
	v_add_u32_e32 v115, 0xfffffb00, v135
	v_lshrrev_b32_e32 v118, 6, v115
	v_lshl_add_u32 v118, v117, 1, v118
	s_movk_i32 s3, 0xef00
	v_ashrrev_i32_e32 v119, 31, v118
	v_mad_u64_u32 v[114:115], s[14:15], v117, s3, v[114:115]
	v_lshlrev_b64 v[118:119], 6, v[118:119]
	v_or_b32_e32 v115, v118, v134
	v_mov_b64_e32 v[120:121], s[60:61]
	s_movk_i32 s3, 0x2200
	v_mad_u64_u32 v[120:121], s[14:15], v115, s3, v[120:121]
	v_mad_i32_i24 v121, v119, s3, v121
	v_ashrrev_i32_e32 v115, 31, v114
	v_lshl_add_u64 v[114:115], v[114:115], 1, v[120:121]
	v_bfe_u32 v120, v203, 5, 1
	v_lshlrev_b32_e32 v120, 3, v120
	v_mov_b32_e32 v121, 0
	v_lshl_add_u64 v[114:115], v[114:115], 0, v[120:121]
	v_cvt_pk_f16_f32 v119, v100, v101
	v_cvt_pk_f16_f32 v118, v98, v99
	global_store_dwordx2 v[114:115], v[118:119], off
	v_cvt_pk_f16_f32 v119, v104, v105
	v_cvt_pk_f16_f32 v118, v102, v103
	global_store_dwordx2 v[114:115], v[118:119], off offset:8
	v_cvt_pk_f16_f32 v119, v108, v109
	v_cvt_pk_f16_f32 v118, v106, v107
	global_store_dwordx2 v[114:115], v[118:119], off offset:32
	v_cvt_pk_f16_f32 v119, v112, v113
	v_cvt_pk_f16_f32 v118, v110, v111
	global_store_dwordx2 v[114:115], v[118:119], off offset:40

; DI void phase_proj(const P& p, int l, char* smem) {
;     ...
;       } else if (nb < 1440) {
;         const int kh = (n - 1312) >> 6, d = (n - 1312) & 63;
;         const int s = srb - b * SA;
;         h16* vt = VgT + ((size_t)(b * 2 + kh) * 64 + d) * SA + s;
; #pragma unroll
;         for (int g = 0; g < 4; ++g) {
;           h16x4 o; o.x = (h16)v[4 * g]; o.y = (h16)v[4 * g + 1]; o.z = (h16)v[4 * g + 2]; o.w = (h16)v[4 * g + 3];
;           *(h16x4*)(vt + 8 * g) = o;
;         }
.LBB0_1157:
	s_andn2_saveexec_b64 s[12:13], s[12:13]
	s_cbranch_execz .LBB0_1159
	v_add_u32_e32 v101, 0xfffffae0, v130
	v_lshrrev_b32_e32 v103, 6, v101
	s_movk_i32 s3, 0xef00
	v_mad_u64_u32 v[98:99], s[14:15], v102, s3, v[98:99]
	v_lshl_add_u32 v102, v102, 1, v103
	v_ashrrev_i32_e32 v103, 31, v102
	v_lshlrev_b64 v[102:103], 6, v[102:103]
	v_and_or_b32 v99, v101, 63, v102
	v_mov_b64_e32 v[104:105], s[60:61]
	s_movk_i32 s3, 0x2200
	v_mad_u64_u32 v[104:105], s[14:15], v99, s3, v[104:105]
	v_mad_i32_i24 v105, v103, s3, v105
	v_ashrrev_i32_e32 v99, 31, v98
	v_lshl_add_u64 v[98:99], v[98:99], 1, v[104:105]
	v_bfe_u32 v104, v203, 5, 1
	v_lshlrev_b32_e32 v104, 3, v104
	v_mov_b32_e32 v105, 0
	v_lshl_add_u64 v[98:99], v[98:99], 0, v[104:105]
	v_cvt_pk_f16_f32 v103, v84, v85
	v_cvt_pk_f16_f32 v102, v82, v83
	global_store_dwordx2 v[98:99], v[102:103], off
	v_cvt_pk_f16_f32 v103, v88, v89
	v_cvt_pk_f16_f32 v102, v86, v87
	global_store_dwordx2 v[98:99], v[102:103], off offset:8
	v_cvt_pk_f16_f32 v103, v92, v93
	v_cvt_pk_f16_f32 v102, v90, v91
	global_store_dwordx2 v[98:99], v[102:103], off offset:32
	v_cvt_pk_f16_f32 v103, v96, v97
	v_cvt_pk_f16_f32 v102, v94, v95
	global_store_dwordx2 v[98:99], v[102:103], off offset:40

; DI void phase_proj(const P& p, int l, char* smem) {
;     ...
;       } else if (nb < 1440) {
;         const int kh = (n - 1312) >> 6, d = (n - 1312) & 63;
;         const int s = srb - b * SA;
;         h16* vt = VgT + ((size_t)(b * 2 + kh) * 64 + d) * SA + s;
; #pragma unroll
;         for (int g = 0; g < 4; ++g) {
;           h16x4 o; o.x = (h16)v[4 * g]; o.y = (h16)v[4 * g + 1]; o.z = (h16)v[4 * g + 2]; o.w = (h16)v[4 * g + 3];
;           *(h16x4*)(vt + 8 * g) = o;
;         }
.LBB0_1314:
	s_andn2_saveexec_b64 s[12:13], s[12:13]
	s_cbranch_execz .LBB0_1316
	v_add_u32_e32 v83, 0xfffffb00, v135
	v_lshrrev_b32_e32 v85, 6, v83
	s_movk_i32 s3, 0xef00
	v_mad_u64_u32 v[82:83], s[14:15], v84, s3, v[82:83]
	v_lshl_add_u32 v84, v84, 1, v85
	v_ashrrev_i32_e32 v85, 31, v84
	v_lshlrev_b64 v[84:85], 6, v[84:85]
	v_or_b32_e32 v83, v84, v134
	v_mov_b64_e32 v[86:87], s[60:61]
	s_movk_i32 s3, 0x2200
	v_mad_u64_u32 v[86:87], s[14:15], v83, s3, v[86:87]
	v_mad_i32_i24 v87, v85, s3, v87
	v_ashrrev_i32_e32 v83, 31, v82
	v_lshl_add_u64 v[82:83], v[82:83], 1, v[86:87]
	v_bfe_u32 v86, v203, 5, 1
	v_lshlrev_b32_e32 v86, 3, v86
	v_mov_b32_e32 v87, 0
	v_lshl_add_u64 v[82:83], v[82:83], 0, v[86:87]
	v_cvt_pk_f16_f32 v85, v68, v69
	v_cvt_pk_f16_f32 v84, v66, v67
	global_store_dwordx2 v[82:83], v[84:85], off
	v_cvt_pk_f16_f32 v85, v72, v73
	v_cvt_pk_f16_f32 v84, v70, v71
	global_store_dwordx2 v[82:83], v[84:85], off offset:8
	v_cvt_pk_f16_f32 v85, v76, v77
	v_cvt_pk_f16_f32 v84, v74, v75
	global_store_dwordx2 v[82:83], v[84:85], off offset:32
	v_cvt_pk_f16_f32 v85, v80, v81
	v_cvt_pk_f16_f32 v84, v78, v79
	global_store_dwordx2 v[82:83], v[84:85], off offset:40

; DI void phase_proj(const P& p, int l, char* smem) {
;     ...
;       } else if (nb < 1440) {
;         const int kh = (n - 1312) >> 6, d = (n - 1312) & 63;
;         const int s = srb - b * SA;
;         h16* vt = VgT + ((size_t)(b * 2 + kh) * 64 + d) * SA + s;
; #pragma unroll
;         for (int g = 0; g < 4; ++g) {
;           h16x4 o; o.x = (h16)v[4 * g]; o.y = (h16)v[4 * g + 1]; o.z = (h16)v[4 * g + 2]; o.w = (h16)v[4 * g + 3];
;           *(h16x4*)(vt + 8 * g) = o;
;         }
.LBB0_1471:
	s_andn2_saveexec_b64 s[12:13], s[12:13]
	s_cbranch_execz .LBB0_1473
	v_add_u32_e32 v69, 0xfffffae0, v130
	v_lshrrev_b32_e32 v71, 6, v69
	s_movk_i32 s3, 0xef00
	v_mad_u64_u32 v[66:67], s[14:15], v70, s3, v[66:67]
	v_lshl_add_u32 v70, v70, 1, v71
	v_ashrrev_i32_e32 v71, 31, v70
	v_lshlrev_b64 v[70:71], 6, v[70:71]
	v_and_or_b32 v67, v69, 63, v70
	v_mov_b64_e32 v[72:73], s[60:61]
	s_movk_i32 s3, 0x2200
	v_mad_u64_u32 v[72:73], s[14:15], v67, s3, v[72:73]
	v_mad_i32_i24 v73, v71, s3, v73
	v_ashrrev_i32_e32 v67, 31, v66
	v_lshl_add_u64 v[66:67], v[66:67], 1, v[72:73]
	v_bfe_u32 v72, v203, 5, 1
	v_lshlrev_b32_e32 v72, 3, v72
	v_mov_b32_e32 v73, 0
	v_lshl_add_u64 v[66:67], v[66:67], 0, v[72:73]
	v_cvt_pk_f16_f32 v71, v52, v53
	v_cvt_pk_f16_f32 v70, v50, v51
	global_store_dwordx2 v[66:67], v[70:71], off
	v_cvt_pk_f16_f32 v71, v56, v57
	v_cvt_pk_f16_f32 v70, v54, v55
	global_store_dwordx2 v[66:67], v[70:71], off offset:8
	v_cvt_pk_f16_f32 v71, v60, v61
	v_cvt_pk_f16_f32 v70, v58, v59
	global_store_dwordx2 v[66:67], v[70:71], off offset:32
	v_cvt_pk_f16_f32 v71, v64, v65
	v_cvt_pk_f16_f32 v70, v62, v63
	global_store_dwordx2 v[66:67], v[70:71], off offset:40

; DI void phase_proj(const P& p, int l, char* smem) {
;     ...
;       } else if (nb < 1440) {
;         const int kh = (n - 1312) >> 6, d = (n - 1312) & 63;
;         const int s = srb - b * SA;
;         h16* vt = VgT + ((size_t)(b * 2 + kh) * 64 + d) * SA + s;
; #pragma unroll
;         for (int g = 0; g < 4; ++g) {
;           h16x4 o; o.x = (h16)v[4 * g]; o.y = (h16)v[4 * g + 1]; o.z = (h16)v[4 * g + 2]; o.w = (h16)v[4 * g + 3];
;           *(h16x4*)(vt + 8 * g) = o;
;         }
.LBB0_1628:
	s_andn2_saveexec_b64 s[12:13], s[12:13]
	s_cbranch_execz .LBB0_1630
	v_add_u32_e32 v51, 0xfffffb00, v135
	v_lshrrev_b32_e32 v53, 6, v51
	s_movk_i32 s3, 0xef00
	v_mad_u64_u32 v[50:51], s[14:15], v52, s3, v[50:51]
	v_lshl_add_u32 v52, v52, 1, v53
	v_ashrrev_i32_e32 v53, 31, v52
	v_lshlrev_b64 v[52:53], 6, v[52:53]
	v_or_b32_e32 v51, v52, v134
	v_mov_b64_e32 v[54:55], s[60:61]
	s_movk_i32 s3, 0x2200
	v_mad_u64_u32 v[54:55], s[14:15], v51, s3, v[54:55]
	v_mad_i32_i24 v55, v53, s3, v55
	v_ashrrev_i32_e32 v51, 31, v50
	v_lshl_add_u64 v[50:51], v[50:51], 1, v[54:55]
	v_bfe_u32 v54, v203, 5, 1
	v_lshlrev_b32_e32 v54, 3, v54
	v_mov_b32_e32 v55, 0
	v_lshl_add_u64 v[50:51], v[50:51], 0, v[54:55]
	v_cvt_pk_f16_f32 v53, v36, v37
	v_cvt_pk_f16_f32 v52, v34, v35
	global_store_dwordx2 v[50:51], v[52:53], off
	v_cvt_pk_f16_f32 v53, v40, v41
	v_cvt_pk_f16_f32 v52, v38, v39
	global_store_dwordx2 v[50:51], v[52:53], off offset:8
	v_cvt_pk_f16_f32 v53, v44, v45
	v_cvt_pk_f16_f32 v52, v42, v43
	global_store_dwordx2 v[50:51], v[52:53], off offset:32
	v_cvt_pk_f16_f32 v53, v48, v49
	v_cvt_pk_f16_f32 v52, v46, v47
	global_store_dwordx2 v[50:51], v[52:53], off offset:40

; DI void phase_proj(const P& p, int l, char* smem) {
;     ...
;       } else if (nb < 1440) {
;         const int kh = (n - 1312) >> 6, d = (n - 1312) & 63;
;         const int s = srb - b * SA;
;         h16* vt = VgT + ((size_t)(b * 2 + kh) * 64 + d) * SA + s;
; #pragma unroll
;         for (int g = 0; g < 4; ++g) {
;           h16x4 o; o.x = (h16)v[4 * g]; o.y = (h16)v[4 * g + 1]; o.z = (h16)v[4 * g + 2]; o.w = (h16)v[4 * g + 3];
;           *(h16x4*)(vt + 8 * g) = o;
;         }
.LBB0_1785:
	s_andn2_saveexec_b64 s[12:13], s[12:13]
	s_cbranch_execz .LBB0_1787
	v_add_u32_e32 v37, 0xfffffae0, v130
	v_lshrrev_b32_e32 v39, 6, v37
	s_movk_i32 s3, 0xef00
	v_mad_u64_u32 v[34:35], s[14:15], v38, s3, v[34:35]
	v_lshl_add_u32 v38, v38, 1, v39
	v_ashrrev_i32_e32 v39, 31, v38
	v_lshlrev_b64 v[38:39], 6, v[38:39]
	v_and_or_b32 v35, v37, 63, v38
	v_mov_b64_e32 v[40:41], s[60:61]
	s_movk_i32 s3, 0x2200
	v_mad_u64_u32 v[40:41], s[14:15], v35, s3, v[40:41]
	v_mad_i32_i24 v41, v39, s3, v41
	v_ashrrev_i32_e32 v35, 31, v34
	v_lshl_add_u64 v[34:35], v[34:35], 1, v[40:41]
	v_bfe_u32 v40, v203, 5, 1
	v_lshlrev_b32_e32 v40, 3, v40
	v_mov_b32_e32 v41, 0
	v_lshl_add_u64 v[34:35], v[34:35], 0, v[40:41]
	v_cvt_pk_f16_f32 v39, v20, v21
	v_cvt_pk_f16_f32 v38, v18, v19
	global_store_dwordx2 v[34:35], v[38:39], off
	v_cvt_pk_f16_f32 v39, v24, v25
	v_cvt_pk_f16_f32 v38, v22, v23
	global_store_dwordx2 v[34:35], v[38:39], off offset:8
	v_cvt_pk_f16_f32 v39, v28, v29
	v_cvt_pk_f16_f32 v38, v26, v27
	global_store_dwordx2 v[34:35], v[38:39], off offset:32
	v_cvt_pk_f16_f32 v39, v32, v33
	v_cvt_pk_f16_f32 v38, v30, v31
	global_store_dwordx2 v[34:35], v[38:39], off offset:40

; DI void phase_proj(const P& p, int l, char* smem) {
;     ...
;       } else if (nb < 1440) {
;         const int kh = (n - 1312) >> 6, d = (n - 1312) & 63;
;         const int s = srb - b * SA;
;         h16* vt = VgT + ((size_t)(b * 2 + kh) * 64 + d) * SA + s;
; #pragma unroll
;         for (int g = 0; g < 4; ++g) {
;           h16x4 o; o.x = (h16)v[4 * g]; o.y = (h16)v[4 * g + 1]; o.z = (h16)v[4 * g + 2]; o.w = (h16)v[4 * g + 3];
;           *(h16x4*)(vt + 8 * g) = o;
;         }
.LBB0_1942:
	s_andn2_saveexec_b64 s[12:13], s[12:13]
	s_cbranch_execz .LBB0_1944
	v_add_u32_e32 v0, 0xfffffb00, v135
	v_lshrrev_b32_e32 v0, 6, v0
	s_movk_i32 s3, 0xef00
	v_mad_u64_u32 v[18:19], s[14:15], v20, s3, v[18:19]
	v_lshl_add_u32 v20, v20, 1, v0
	v_ashrrev_i32_e32 v21, 31, v20
	v_lshlrev_b64 v[20:21], 6, v[20:21]
	v_or_b32_e32 v0, v20, v134
	v_mov_b64_e32 v[22:23], s[60:61]
	s_movk_i32 s3, 0x2200
	v_mad_u64_u32 v[22:23], s[14:15], v0, s3, v[22:23]
	v_mad_i32_i24 v23, v21, s3, v23
	v_ashrrev_i32_e32 v19, 31, v18
	v_lshl_add_u64 v[18:19], v[18:19], 1, v[22:23]
	v_bfe_u32 v22, v203, 5, 1
	v_lshlrev_b32_e32 v22, 3, v22
	v_mov_b32_e32 v23, 0
	v_lshl_add_u64 v[18:19], v[18:19], 0, v[22:23]
	v_cvt_pk_f16_f32 v21, v4, v5
	v_cvt_pk_f16_f32 v20, v2, v3
	global_store_dwordx2 v[18:19], v[20:21], off
	v_cvt_pk_f16_f32 v21, v8, v9
	v_cvt_pk_f16_f32 v20, v6, v7
	global_store_dwordx2 v[18:19], v[20:21], off offset:8
	v_cvt_pk_f16_f32 v21, v12, v13
	v_cvt_pk_f16_f32 v20, v10, v11
	global_store_dwordx2 v[18:19], v[20:21], off offset:32
	v_cvt_pk_f16_f32 v21, v16, v17
	v_cvt_pk_f16_f32 v20, v14, v15
	global_store_dwordx2 v[18:19], v[20:21], off offset:40

; template <class BR>
; DI void gemm_tile_w(const h16* __restrict__ A, int lda, const h16* __restrict__ B, int ldb, BR brow, int K, f32x16 (&acc)[4][2], h16* sm) {
;   const int tid = TIDX(), lane = tid & 63, w = tid >> 6, wm = w >> 1, wn = w & 1, r = lane & 31, hh = lane >> 5;
;   const unsigned ao = (unsigned)(tid >> 2) * (unsigned)lda + (unsigned)(tid & 3) * 8u;
;   const unsigned bo0 = (unsigned)brow(tid >> 2) * (unsigned)ldb + (unsigned)(tid & 3) * 8u;
;   const unsigned bo1 = (unsigned)brow((tid >> 2) + 64) * (unsigned)ldb + (unsigned)(tid & 3) * 8u;
;   const h16* ag = A;
;   const h16* bg = B;
;   u32x4 ra0[4], rb0[2], ra1[4], rb1[2];
; #pragma unroll
;   for (int i = 0; i < 4; ++i) ra0[i] = *(const u32x4*)(ag + (ao + (unsigned)i * 64u * (unsigned)lda));
;   rb0[0] = *(const u32x4*)(bg + bo0);
;   rb0[1] = *(const u32x4*)(bg + bo1);
;   ag += 32; bg += 32;
; #pragma unroll
;   for (int i = 0; i < 4; ++i) ra1[i] = *(const u32x4*)(ag + (ao + (unsigned)i * 64u * (unsigned)lda));
;   rb1[0] = *(const u32x4*)(bg + bo0);
;   rb1[1] = *(const u32x4*)(bg + bo1);
;   const int nk = K >> 5;
;   const int wofs = (tid >> 2) * LS2 + (tid & 3) * 8;
;     ...
;   for (int kt = 0; kt < nk; kt += 2) {
;     WIDE_HALF(ra0, rb0, 0, kt)
;     WIDE_HALF(ra1, rb1, 1, kt + 1)
; DI void phase_uproj(const P& p, int l, char* smem, int boff, int geff) {
;     ...
;   for (int u_ = be_ >> 3; u_ < Mx_ * 14; u_ += (geff >> 3)) {
;     int mt_, nn;
;     tile_map(u_, Mx_, 14, xcd_, mt_, nn);
;     if (mt_ >= 136) continue;
;     const int m0 = mt_ * 256;
;     f32x16 acc[4][2];
;     zero_acc_w(acc);
;     if (nn < 6) {
;       const int n0 = nn * 128;
;       gemm_tile_w(cqkv + (size_t)m0 * 640, 640, W + WO_UQ, 384, [&](int rr) { return n0 + rr; }, 384, acc, (h16*)smem);
;       epi_foreach_w(acc, m0, n0, [&](int rbase, int n, const f32x16& v) {
;         const int b = rbase < TL ? (rbase >> 12) : ((rbase - TL) >> 8);
;         const int srb = srow_of(rbase);
;         const int head = n / 96, dd = n - head * 96;
;         h16* q = Qm + ((size_t)(b * 7 + head) * SA) * 96 + dd;
;         if (dd < 64 || rbase >= TL) {
; #pragma unroll
;           for (int i = 0; i < 16; ++i) q[(size_t)EROW(srb, i) * 96] = (h16)(v[i] * qscale);
;         } else {
;           const int ii = dd - 64;
; #pragma unroll
;           for (int i = 0; i < 16; ++i) {
;             float x = v[i];
.LBB0_2115:
	s_mul_hi_i32 s0, s36, 0x92492493
	s_add_i32 s0, s0, s36
	s_lshr_b32 s1, s0, 31
	s_ashr_i32 s0, s0, 6
	s_add_i32 s1, s0, s1
	s_lshl_b32 s0, s1, 3
	s_sub_i32 s0, 17, s0
	s_min_u32 s20, s0, 8
	v_cvt_f32_ubyte0_e32 v0, s20
	v_rcp_iflag_f32_e32 v0, v0
	s_mul_i32 s0, s1, 0xffffff90
	s_add_i32 s0, s36, s0
	s_ashr_i32 s0, s0, 31
	v_mul_f32_e32 v0, 0x4f7ffffe, v0
	v_cvt_u32_f32_e32 v0, v0
	s_mul_i32 s21, s1, 0x70
	s_sub_i32 s22, 0, s20
	s_sub_i32 s21, s0, s21
	v_readfirstlane_b32 s23, v0
	s_mul_i32 s22, s22, s23
	s_add_i32 s21, s36, s21
	s_mul_hi_u32 s22, s23, s22
	s_xor_b32 s21, s21, s0
	s_add_i32 s23, s23, s22
	s_mul_hi_u32 s22, s21, s23
	s_mul_i32 s23, s22, s20
	s_sub_i32 s21, s21, s23
	s_add_i32 s23, s22, 1
	s_sub_i32 s24, s21, s20
	s_cmp_ge_u32 s21, s20
	s_cselect_b32 s22, s23, s22
	s_cselect_b32 s21, s24, s21
	s_add_i32 s23, s22, 1
	s_cmp_ge_u32 s21, s20
	s_cselect_b32 s21, s23, s22
	s_xor_b32 s21, s21, s0
	s_sub_i32 s0, s21, s0
	s_mul_i32 s20, s20, s0
	s_mulk_i32 s1, 0x68
	s_add_i32 s20, s20, s1
	s_add_i32 s1, s86, s36
	s_sub_i32 s1, s1, s20
	s_cmpk_gt_i32 s1, 0x87
	s_cbranch_scc1 .LBB0_2114
	s_lshl_b32 s21, s1, 8
	s_lshl_b32 s20, s0, 7
	s_cmp_gt_i32 s0, 5
	s_mov_b64 s[0:1], -1
	s_mul_hi_i32 s22, s21, 0x500
	s_mul_i32 s23, s21, 0x500
	s_cbranch_scc0 .LBB0_2182
	v_mov_b32_e32 v30, v203
	s_add_i32 s24, s20, 0xfffffd00
	s_add_u32 s0, s69, s23
	v_ashrrev_i32_e32 v31, 2, v30
	v_lshlrev_b32_e32 v2, 3, v30
	v_mul_lo_u32 v0, v31, s67
	v_and_b32_e32 v32, 24, v2
	s_addc_u32 s1, s83, s22
	v_or_b32_e32 v0, v0, v32
	v_add_u32_e32 v18, s24, v31
	v_lshl_add_u64 v[132:133], v[0:1], 1, s[0:1]
	v_add_u32_e32 v6, 0xa000, v0
	v_mov_b32_e32 v7, v1
	v_add_u32_e32 v10, 0x14000, v0
	v_add_u32_e32 v0, 0x1e000, v0
	global_load_dwordx4 v[2:5], v[132:133], off offset:768
	v_lshl_add_u64 v[134:135], v[6:7], 1, s[0:1]
	v_mov_b32_e32 v11, v1
	v_lshl_add_u64 v[138:139], v[0:1], 1, s[0:1]
	v_lshl_or_b32 v0, v18, 8, v32
	global_load_dwordx4 v[6:9], v[134:135], off offset:768
	v_lshl_add_u64 v[136:137], v[10:11], 1, s[0:1]
	v_add_u32_e32 v18, 0x4000, v0
	v_mov_b32_e32 v19, v1
	global_load_dwordx4 v[10:13], v[136:137], off offset:768
	global_load_dwordx4 v[14:17], v[138:139], off offset:768
	v_lshlrev_b64 v[140:141], 1, v[0:1]
	s_waitcnt vmcnt(8)
	v_lshlrev_b64 v[142:143], 1, v[18:19]
	v_lshl_add_u64 v[20:21], s[56:57], 0, v[140:141]
	v_lshl_add_u64 v[22:23], s[56:57], 0, v[142:143]
	global_load_dwordx4 v[18:21], v[20:21], off
	s_nop 0
	global_load_dwordx4 v[22:25], v[22:23], off
	s_nop 0
	global_load_dwordx4 v[144:147], v[132:133], off offset:832
	global_load_dwordx4 v[148:151], v[134:135], off offset:832
	global_load_dwordx4 v[152:155], v[136:137], off offset:832
	global_load_dwordx4 v[156:159], v[138:139], off offset:832
	v_lshl_add_u64 v[26:27], s[58:59], 0, v[140:141]
	v_lshl_add_u64 v[28:29], s[58:59], 0, v[142:143]
	global_load_dwordx4 v[160:163], v[26:27], off
	global_load_dwordx4 v[164:167], v[28:29], off
	v_lshrrev_b32_e32 v0, 1, v30
	v_and_b32_e32 v26, 0xfffff9f, v30
	v_and_b32_e32 v27, 0x5f, v30
	v_mul_lo_u32 v28, v31, 40
	v_and_b32_e32 v0, 16, v0
	v_mul_u32_u24_e32 v27, 40, v27
	v_add_lshl_u32 v202, v28, v32, 1
	v_mad_u64_u32 v[130:131], s[0:1], v26, s76, v[0:1]
	v_lshl_add_u32 v0, v27, 1, v0
	s_waitcnt vmcnt(11)
	ds_write_b128 v202, v[2:5]
	s_waitcnt vmcnt(10)
	ds_write_b128 v202, v[6:9] offset:5120
	s_waitcnt vmcnt(9)
	ds_write_b128 v202, v[10:13] offset:10240
	s_waitcnt vmcnt(8)
	ds_write_b128 v202, v[14:17] offset:15360
	s_waitcnt vmcnt(7)
	ds_write_b128 v202, v[18:21] offset:20480
	s_waitcnt vmcnt(6)
	ds_write_b128 v202, v[22:25] offset:25600
	s_waitcnt lgkmcnt(0)
	s_barrier
	ds_read_b128 v[2:5], v130
	ds_read_b128 v[6:9], v130 offset:2560
	ds_read_b128 v[10:13], v130 offset:5120
	ds_read_b128 v[14:17], v130 offset:7680
	ds_read_b128 v[18:21], v0 offset:20480
	ds_read_b128 v[168:171], v0 offset:23040
	global_load_dwordx4 v[172:175], v[132:133], off offset:896
	global_load_dwordx4 v[176:179], v[134:135], off offset:896
	global_load_dwordx4 v[180:183], v[136:137], off offset:896
	global_load_dwordx4 v[184:187], v[138:139], off offset:896
	v_lshl_add_u64 v[22:23], s[80:81], 0, v[140:141]
	v_lshl_add_u64 v[24:25], s[80:81], 0, v[142:143]
	global_load_dwordx4 v[188:191], v[22:23], off
	global_load_dwordx4 v[192:195], v[24:25], off
	ds_read_b128 v[196:199], v130 offset:32
	ds_read_b128 v[204:207], v130 offset:2592
	ds_read_b128 v[208:211], v130 offset:5152
	ds_read_b128 v[212:215], v130 offset:7712
	ds_read_b128 v[238:241], v0 offset:20512
	ds_read_b128 v[242:245], v0 offset:23072
	s_waitcnt lgkmcnt(7)
	v_mfma_f32_32x32x16_f16 v[114:129], v[2:5], v[18:21], 0
	s_waitcnt lgkmcnt(6)
	v_mfma_f32_32x32x16_f16 v[98:113], v[2:5], v[168:171], 0
	v_mfma_f32_32x32x16_f16 v[82:97], v[6:9], v[18:21], 0
	v_mfma_f32_32x32x16_f16 v[66:81], v[6:9], v[168:171], 0
	v_mfma_f32_32x32x16_f16 v[50:65], v[10:13], v[18:21], 0
	v_mfma_f32_32x32x16_f16 v[34:49], v[10:13], v[168:171], 0
	v_mfma_f32_32x32x16_f16 v[18:33], v[14:17], v[18:21], 0
	v_mfma_f32_32x32x16_f16 v[2:17], v[14:17], v[168:171], 0
	s_waitcnt lgkmcnt(1)
	v_mfma_f32_32x32x16_f16 v[114:129], v[196:199], v[238:241], v[114:129]
	s_waitcnt lgkmcnt(0)
	v_mfma_f32_32x32x16_f16 v[98:113], v[196:199], v[242:245], v[98:113]
	v_mfma_f32_32x32x16_f16 v[82:97], v[204:207], v[238:241], v[82:97]
	v_mfma_f32_32x32x16_f16 v[66:81], v[204:207], v[242:245], v[66:81]
	v_mfma_f32_32x32x16_f16 v[50:65], v[208:211], v[238:241], v[50:65]
	v_mfma_f32_32x32x16_f16 v[34:49], v[208:211], v[242:245], v[34:49]
	v_mfma_f32_32x32x16_f16 v[18:33], v[212:215], v[238:241], v[18:33]
	v_mfma_f32_32x32x16_f16 v[2:17], v[212:215], v[242:245], v[2:17]
	s_waitcnt vmcnt(11)
	ds_write_b128 v202, v[144:147] offset:30720
	s_waitcnt vmcnt(10)
	ds_write_b128 v202, v[148:151] offset:35840
	s_waitcnt vmcnt(9)
	ds_write_b128 v202, v[152:155] offset:40960
	s_waitcnt vmcnt(8)
	ds_write_b128 v202, v[156:159] offset:46080
	s_waitcnt vmcnt(7)
	ds_write_b128 v202, v[160:163] offset:51200
	s_waitcnt vmcnt(6)
	ds_write_b128 v202, v[164:167] offset:56320
	s_waitcnt lgkmcnt(0)
	s_barrier
; DI int TIDX() { int t = threadIdx.x; asm volatile("" : "+v"(t)); return t; }
; template <class BR>
; DI void gemm_tile_w(const h16* __restrict__ A, int lda, const h16* __restrict__ B, int ldb, BR brow, int K, f32x16 (&acc)[4][2], h16* sm) {
;   const int tid = TIDX(), lane = tid & 63, w = tid >> 6, wm = w >> 1, wn = w & 1, r = lane & 31, hh = lane >> 5;
;   const unsigned ao = (unsigned)(tid >> 2) * (unsigned)lda + (unsigned)(tid & 3) * 8u;
;   const unsigned bo0 = (unsigned)brow(tid >> 2) * (unsigned)ldb + (unsigned)(tid & 3) * 8u;
;   const unsigned bo1 = (unsigned)brow((tid >> 2) + 64) * (unsigned)ldb + (unsigned)(tid & 3) * 8u;
;   const h16* ag = A;
;   const h16* bg = B;
;   u32x4 ra0[4], rb0[2], ra1[4], rb1[2];
; #pragma unroll
;   for (int i = 0; i < 4; ++i) ra0[i] = *(const u32x4*)(ag + (ao + (unsigned)i * 64u * (unsigned)lda));
;   rb0[0] = *(const u32x4*)(bg + bo0);
;   rb0[1] = *(const u32x4*)(bg + bo1);
;   ag += 32; bg += 32;
; #pragma unroll
;   for (int i = 0; i < 4; ++i) ra1[i] = *(const u32x4*)(ag + (ao + (unsigned)i * 64u * (unsigned)lda));
;   rb1[0] = *(const u32x4*)(bg + bo0);
;   rb1[1] = *(const u32x4*)(bg + bo1);
;   const int nk = K >> 5;
;   const int wofs = (tid >> 2) * LS2 + (tid & 3) * 8;
;     ...
;   for (int kt = 0; kt < nk; kt += 2) {
;     WIDE_HALF(ra0, rb0, 0, kt)
;     WIDE_HALF(ra1, rb1, 1, kt + 1)
	ds_read_b128 v[144:147], v130 offset:33280
	ds_read_b128 v[148:151], v130 offset:35840
	ds_read_b128 v[152:155], v130 offset:30720
	ds_read_b128 v[156:159], v130 offset:38400
	ds_read_b128 v[160:163], v0 offset:51200
	ds_read_b128 v[164:167], v0 offset:53760
	global_load_dwordx4 v[168:171], v[132:133], off offset:960
	global_load_dwordx4 v[196:199], v[134:135], off offset:960
	global_load_dwordx4 v[204:207], v[136:137], off offset:960
	global_load_dwordx4 v[208:211], v[138:139], off offset:960
	v_lshl_add_u64 v[200:201], s[84:85], 0, v[140:141]
	v_lshl_add_u64 v[216:217], s[84:85], 0, v[142:143]
	global_load_dwordx4 v[212:215], v[200:201], off
	global_load_dwordx4 v[238:241], v[216:217], off
	s_waitcnt lgkmcnt(1)
	v_mfma_f32_32x32x16_f16 v[114:129], v[152:155], v[160:163], v[114:129]
	s_waitcnt lgkmcnt(0)
	v_mfma_f32_32x32x16_f16 v[98:113], v[152:155], v[164:167], v[98:113]
	v_mfma_f32_32x32x16_f16 v[82:97], v[144:147], v[160:163], v[82:97]
	v_mfma_f32_32x32x16_f16 v[66:81], v[144:147], v[164:167], v[66:81]
	v_mfma_f32_32x32x16_f16 v[50:65], v[148:151], v[160:163], v[50:65]
	v_mfma_f32_32x32x16_f16 v[34:49], v[148:151], v[164:167], v[34:49]
	v_mfma_f32_32x32x16_f16 v[18:33], v[156:159], v[160:163], v[18:33]
	ds_read_b128 v[144:147], v130 offset:33312
	ds_read_b128 v[148:151], v130 offset:35872
	ds_read_b128 v[152:155], v130 offset:30752
	ds_read_b128 v[160:163], v130 offset:38432
	ds_read_b128 v[242:245], v0 offset:51232
	ds_read_b128 v[246:249], v0 offset:53792
	v_mfma_f32_32x32x16_f16 v[2:17], v[156:159], v[164:167], v[2:17]
	s_waitcnt lgkmcnt(1)
	v_mfma_f32_32x32x16_f16 v[114:129], v[152:155], v[242:245], v[114:129]
	s_waitcnt lgkmcnt(0)
	v_mfma_f32_32x32x16_f16 v[98:113], v[152:155], v[246:249], v[98:113]
	v_mfma_f32_32x32x16_f16 v[82:97], v[144:147], v[242:245], v[82:97]
	v_mfma_f32_32x32x16_f16 v[66:81], v[144:147], v[246:249], v[66:81]
	v_mfma_f32_32x32x16_f16 v[50:65], v[148:151], v[242:245], v[50:65]
	v_mfma_f32_32x32x16_f16 v[34:49], v[148:151], v[246:249], v[34:49]
	v_mfma_f32_32x32x16_f16 v[18:33], v[160:163], v[242:245], v[18:33]
	v_mfma_f32_32x32x16_f16 v[2:17], v[160:163], v[246:249], v[2:17]
	s_waitcnt vmcnt(11)
	ds_write_b128 v202, v[172:175]
	s_waitcnt vmcnt(10)
	ds_write_b128 v202, v[176:179] offset:5120
	s_waitcnt vmcnt(9)
	ds_write_b128 v202, v[180:183] offset:10240
	s_waitcnt vmcnt(8)
	ds_write_b128 v202, v[184:187] offset:15360
	s_waitcnt vmcnt(7)
	ds_write_b128 v202, v[188:191] offset:20480
	s_waitcnt vmcnt(6)
	ds_write_b128 v202, v[192:195] offset:25600
	s_waitcnt lgkmcnt(0)
	s_barrier
	ds_read_b128 v[144:147], v130
	ds_read_b128 v[148:151], v130 offset:2560
	ds_read_b128 v[152:155], v130 offset:5120
	ds_read_b128 v[156:159], v130 offset:7680
	ds_read_b128 v[160:163], v0 offset:20480
	ds_read_b128 v[164:167], v0 offset:23040
	global_load_dwordx4 v[172:175], v[132:133], off offset:1024
	global_load_dwordx4 v[176:179], v[134:135], off offset:1024
	global_load_dwordx4 v[180:183], v[136:137], off offset:1024
	global_load_dwordx4 v[184:187], v[138:139], off offset:1024
	v_lshl_add_u64 v[188:189], s[88:89], 0, v[140:141]
	v_lshl_add_u64 v[192:193], s[88:89], 0, v[142:143]
	global_load_dwordx4 v[188:191], v[188:189], off
	s_nop 0
	global_load_dwordx4 v[192:195], v[192:193], off
	s_waitcnt lgkmcnt(1)
	v_mfma_f32_32x32x16_f16 v[114:129], v[144:147], v[160:163], v[114:129]
	s_waitcnt lgkmcnt(0)
	v_mfma_f32_32x32x16_f16 v[98:113], v[144:147], v[164:167], v[98:113]
	v_mfma_f32_32x32x16_f16 v[82:97], v[148:151], v[160:163], v[82:97]
	v_mfma_f32_32x32x16_f16 v[66:81], v[148:151], v[164:167], v[66:81]
	v_mfma_f32_32x32x16_f16 v[50:65], v[152:155], v[160:163], v[50:65]
	v_mfma_f32_32x32x16_f16 v[34:49], v[152:155], v[164:167], v[34:49]
	v_mfma_f32_32x32x16_f16 v[18:33], v[156:159], v[160:163], v[18:33]
	ds_read_b128 v[144:147], v130 offset:32
	ds_read_b128 v[148:151], v130 offset:2592
	ds_read_b128 v[152:155], v130 offset:5152
	ds_read_b128 v[160:163], v130 offset:7712
	ds_read_b128 v[242:245], v0 offset:20512
	ds_read_b128 v[246:249], v0 offset:23072
	v_mfma_f32_32x32x16_f16 v[2:17], v[156:159], v[164:167], v[2:17]
	s_waitcnt lgkmcnt(1)
	v_mfma_f32_32x32x16_f16 v[114:129], v[144:147], v[242:245], v[114:129]
	s_waitcnt lgkmcnt(0)
	v_mfma_f32_32x32x16_f16 v[98:113], v[144:147], v[246:249], v[98:113]
	v_mfma_f32_32x32x16_f16 v[82:97], v[148:151], v[242:245], v[82:97]
	v_mfma_f32_32x32x16_f16 v[66:81], v[148:151], v[246:249], v[66:81]
	v_mfma_f32_32x32x16_f16 v[50:65], v[152:155], v[242:245], v[50:65]
	v_mfma_f32_32x32x16_f16 v[34:49], v[152:155], v[246:249], v[34:49]
	v_mfma_f32_32x32x16_f16 v[18:33], v[160:163], v[242:245], v[18:33]
	v_mfma_f32_32x32x16_f16 v[2:17], v[160:163], v[246:249], v[2:17]
	s_waitcnt vmcnt(11)
	ds_write_b128 v202, v[168:171] offset:30720
	s_waitcnt vmcnt(10)
	ds_write_b128 v202, v[196:199] offset:35840
	s_waitcnt vmcnt(9)
	ds_write_b128 v202, v[204:207] offset:40960
	s_waitcnt vmcnt(8)
	ds_write_b128 v202, v[208:211] offset:46080
	s_waitcnt vmcnt(7)
	ds_write_b128 v202, v[212:215] offset:51200
	s_waitcnt vmcnt(6)
	ds_write_b128 v202, v[238:241] offset:56320
	s_waitcnt lgkmcnt(0)
	s_barrier
; DI int TIDX() { int t = threadIdx.x; asm volatile("" : "+v"(t)); return t; }
; template <class BR>
; DI void gemm_tile_w(const h16* __restrict__ A, int lda, const h16* __restrict__ B, int ldb, BR brow, int K, f32x16 (&acc)[4][2], h16* sm) {
;   const int tid = TIDX(), lane = tid & 63, w = tid >> 6, wm = w >> 1, wn = w & 1, r = lane & 31, hh = lane >> 5;
;   const unsigned ao = (unsigned)(tid >> 2) * (unsigned)lda + (unsigned)(tid & 3) * 8u;
;   const unsigned bo0 = (unsigned)brow(tid >> 2) * (unsigned)ldb + (unsigned)(tid & 3) * 8u;
;   const unsigned bo1 = (unsigned)brow((tid >> 2) + 64) * (unsigned)ldb + (unsigned)(tid & 3) * 8u;
;   const h16* ag = A;
;   const h16* bg = B;
;   u32x4 ra0[4], rb0[2], ra1[4], rb1[2];
; #pragma unroll
;   for (int i = 0; i < 4; ++i) ra0[i] = *(const u32x4*)(ag + (ao + (unsigned)i * 64u * (unsigned)lda));
;   rb0[0] = *(const u32x4*)(bg + bo0);
;   rb0[1] = *(const u32x4*)(bg + bo1);
;   ag += 32; bg += 32;
; #pragma unroll
;   for (int i = 0; i < 4; ++i) ra1[i] = *(const u32x4*)(ag + (ao + (unsigned)i * 64u * (unsigned)lda));
;   rb1[0] = *(const u32x4*)(bg + bo0);
;   rb1[1] = *(const u32x4*)(bg + bo1);
;   const int nk = K >> 5;
;   const int wofs = (tid >> 2) * LS2 + (tid & 3) * 8;
;     ...
;   for (int kt = 0; kt < nk; kt += 2) {
;     WIDE_HALF(ra0, rb0, 0, kt)
;     WIDE_HALF(ra1, rb1, 1, kt + 1)
	ds_read_b128 v[144:147], v130 offset:33280
	ds_read_b128 v[148:151], v130 offset:35840
	ds_read_b128 v[152:155], v130 offset:30720
	ds_read_b128 v[156:159], v130 offset:38400
	ds_read_b128 v[160:163], v0 offset:51200
	ds_read_b128 v[164:167], v0 offset:53760
	global_load_dwordx4 v[168:171], v[132:133], off offset:1088
	global_load_dwordx4 v[196:199], v[134:135], off offset:1088
	global_load_dwordx4 v[204:207], v[136:137], off offset:1088
	global_load_dwordx4 v[208:211], v[138:139], off offset:1088
	s_mov_b64 s[0:1], s[54:55]
	v_lshl_add_u64 v[200:201], s[0:1], 0, v[140:141]
	v_lshl_add_u64 v[216:217], s[0:1], 0, v[142:143]
	global_load_dwordx4 v[212:215], v[200:201], off
	global_load_dwordx4 v[238:241], v[216:217], off
	s_waitcnt lgkmcnt(1)
	v_mfma_f32_32x32x16_f16 v[114:129], v[152:155], v[160:163], v[114:129]
	s_waitcnt lgkmcnt(0)
	v_mfma_f32_32x32x16_f16 v[98:113], v[152:155], v[164:167], v[98:113]
	v_mfma_f32_32x32x16_f16 v[82:97], v[144:147], v[160:163], v[82:97]
	v_mfma_f32_32x32x16_f16 v[66:81], v[144:147], v[164:167], v[66:81]
	v_mfma_f32_32x32x16_f16 v[50:65], v[148:151], v[160:163], v[50:65]
	v_mfma_f32_32x32x16_f16 v[34:49], v[148:151], v[164:167], v[34:49]
	v_mfma_f32_32x32x16_f16 v[18:33], v[156:159], v[160:163], v[18:33]
	ds_read_b128 v[144:147], v130 offset:33312
	ds_read_b128 v[148:151], v130 offset:35872
	ds_read_b128 v[152:155], v130 offset:30752
	ds_read_b128 v[160:163], v130 offset:38432
	ds_read_b128 v[242:245], v0 offset:51232
	ds_read_b128 v[246:249], v0 offset:53792
	v_mfma_f32_32x32x16_f16 v[2:17], v[156:159], v[164:167], v[2:17]
	s_waitcnt lgkmcnt(1)
	v_mfma_f32_32x32x16_f16 v[114:129], v[152:155], v[242:245], v[114:129]
	s_waitcnt lgkmcnt(0)
	v_mfma_f32_32x32x16_f16 v[98:113], v[152:155], v[246:249], v[98:113]
	v_mfma_f32_32x32x16_f16 v[82:97], v[144:147], v[242:245], v[82:97]
	v_mfma_f32_32x32x16_f16 v[66:81], v[144:147], v[246:249], v[66:81]
	v_mfma_f32_32x32x16_f16 v[50:65], v[148:151], v[242:245], v[50:65]
	v_mfma_f32_32x32x16_f16 v[34:49], v[148:151], v[246:249], v[34:49]
	v_mfma_f32_32x32x16_f16 v[18:33], v[160:163], v[242:245], v[18:33]
	v_mfma_f32_32x32x16_f16 v[2:17], v[160:163], v[246:249], v[2:17]
	s_waitcnt vmcnt(11)
	ds_write_b128 v202, v[172:175]
	s_waitcnt vmcnt(10)
	ds_write_b128 v202, v[176:179] offset:5120
	s_waitcnt vmcnt(9)
	ds_write_b128 v202, v[180:183] offset:10240
	s_waitcnt vmcnt(8)
	ds_write_b128 v202, v[184:187] offset:15360
	s_waitcnt vmcnt(7)
	ds_write_b128 v202, v[188:191] offset:20480
	s_waitcnt vmcnt(6)
	ds_write_b128 v202, v[192:195] offset:25600
	s_waitcnt lgkmcnt(0)
	s_barrier
	ds_read_b128 v[144:147], v130
	ds_read_b128 v[148:151], v130 offset:2560
	ds_read_b128 v[152:155], v130 offset:5120
	ds_read_b128 v[156:159], v130 offset:7680
	ds_read_b128 v[160:163], v0 offset:20480
	ds_read_b128 v[164:167], v0 offset:23040
	global_load_dwordx4 v[172:175], v[132:133], off offset:1152
	global_load_dwordx4 v[176:179], v[134:135], off offset:1152
	global_load_dwordx4 v[180:183], v[136:137], off offset:1152
	global_load_dwordx4 v[184:187], v[138:139], off offset:1152
	s_mov_b64 s[0:1], s[70:71]
	v_lshl_add_u64 v[188:189], s[0:1], 0, v[140:141]
	v_lshl_add_u64 v[192:193], s[0:1], 0, v[142:143]
	global_load_dwordx4 v[188:191], v[188:189], off
	s_nop 0
	global_load_dwordx4 v[192:195], v[192:193], off
	s_waitcnt lgkmcnt(1)
	v_mfma_f32_32x32x16_f16 v[114:129], v[144:147], v[160:163], v[114:129]
	s_waitcnt lgkmcnt(0)
	v_mfma_f32_32x32x16_f16 v[98:113], v[144:147], v[164:167], v[98:113]
	v_mfma_f32_32x32x16_f16 v[82:97], v[148:151], v[160:163], v[82:97]
	v_mfma_f32_32x32x16_f16 v[66:81], v[148:151], v[164:167], v[66:81]
	v_mfma_f32_32x32x16_f16 v[50:65], v[152:155], v[160:163], v[50:65]
	v_mfma_f32_32x32x16_f16 v[34:49], v[152:155], v[164:167], v[34:49]
	v_mfma_f32_32x32x16_f16 v[18:33], v[156:159], v[160:163], v[18:33]
	ds_read_b128 v[144:147], v130 offset:32
	ds_read_b128 v[148:151], v130 offset:2592
	ds_read_b128 v[152:155], v130 offset:5152
	ds_read_b128 v[160:163], v130 offset:7712
	ds_read_b128 v[242:245], v0 offset:20512
	ds_read_b128 v[246:249], v0 offset:23072
	v_mfma_f32_32x32x16_f16 v[2:17], v[156:159], v[164:167], v[2:17]
	s_waitcnt lgkmcnt(1)
	v_mfma_f32_32x32x16_f16 v[114:129], v[144:147], v[242:245], v[114:129]
	s_waitcnt lgkmcnt(0)
	v_mfma_f32_32x32x16_f16 v[98:113], v[144:147], v[246:249], v[98:113]
	v_mfma_f32_32x32x16_f16 v[82:97], v[148:151], v[242:245], v[82:97]
	v_mfma_f32_32x32x16_f16 v[66:81], v[148:151], v[246:249], v[66:81]
	v_mfma_f32_32x32x16_f16 v[50:65], v[152:155], v[242:245], v[50:65]
	v_mfma_f32_32x32x16_f16 v[34:49], v[152:155], v[246:249], v[34:49]
	v_mfma_f32_32x32x16_f16 v[18:33], v[160:163], v[242:245], v[18:33]
	v_mfma_f32_32x32x16_f16 v[2:17], v[160:163], v[246:249], v[2:17]
	s_waitcnt vmcnt(11)
	ds_write_b128 v202, v[168:171] offset:30720
	s_waitcnt vmcnt(10)
	ds_write_b128 v202, v[196:199] offset:35840
	s_waitcnt vmcnt(9)
	ds_write_b128 v202, v[204:207] offset:40960
	s_waitcnt vmcnt(8)
	ds_write_b128 v202, v[208:211] offset:46080
	s_waitcnt vmcnt(7)
	ds_write_b128 v202, v[212:215] offset:51200
	s_waitcnt vmcnt(6)
	ds_write_b128 v202, v[238:241] offset:56320
	s_waitcnt lgkmcnt(0)
	s_barrier
; DI int TIDX() { int t = threadIdx.x; asm volatile("" : "+v"(t)); return t; }
; template <class BR>
; DI void gemm_tile_w(const h16* __restrict__ A, int lda, const h16* __restrict__ B, int ldb, BR brow, int K, f32x16 (&acc)[4][2], h16* sm) {
;   const int tid = TIDX(), lane = tid & 63, w = tid >> 6, wm = w >> 1, wn = w & 1, r = lane & 31, hh = lane >> 5;
;   const unsigned ao = (unsigned)(tid >> 2) * (unsigned)lda + (unsigned)(tid & 3) * 8u;
;   const unsigned bo0 = (unsigned)brow(tid >> 2) * (unsigned)ldb + (unsigned)(tid & 3) * 8u;
;   const unsigned bo1 = (unsigned)brow((tid >> 2) + 64) * (unsigned)ldb + (unsigned)(tid & 3) * 8u;
;   const h16* ag = A;
;   const h16* bg = B;
;   u32x4 ra0[4], rb0[2], ra1[4], rb1[2];
; #pragma unroll
;   for (int i = 0; i < 4; ++i) ra0[i] = *(const u32x4*)(ag + (ao + (unsigned)i * 64u * (unsigned)lda));
;   rb0[0] = *(const u32x4*)(bg + bo0);
;   rb0[1] = *(const u32x4*)(bg + bo1);
;   ag += 32; bg += 32;
; #pragma unroll
;   for (int i = 0; i < 4; ++i) ra1[i] = *(const u32x4*)(ag + (ao + (unsigned)i * 64u * (unsigned)lda));
;   rb1[0] = *(const u32x4*)(bg + bo0);
;   rb1[1] = *(const u32x4*)(bg + bo1);
;   const int nk = K >> 5;
;   const int wofs = (tid >> 2) * LS2 + (tid & 3) * 8;
;     ...
;   for (int kt = 0; kt < nk; kt += 2) {
;     WIDE_HALF(ra0, rb0, 0, kt)
;     WIDE_HALF(ra1, rb1, 1, kt + 1)
	ds_read_b128 v[144:147], v130 offset:33280
	ds_read_b128 v[148:151], v130 offset:35840
	ds_read_b128 v[152:155], v130 offset:30720
	ds_read_b128 v[156:159], v130 offset:38400
	ds_read_b128 v[160:163], v0 offset:51200
	ds_read_b128 v[164:167], v0 offset:53760
	global_load_dwordx4 v[168:171], v[132:133], off offset:1216
	s_nop 0
	global_load_dwordx4 v[132:135], v[134:135], off offset:1216
	s_nop 0
	global_load_dwordx4 v[196:199], v[136:137], off offset:1216
	s_nop 0
	global_load_dwordx4 v[136:139], v[138:139], off offset:1216
	v_lshl_add_u64 v[140:141], s[16:17], 0, v[140:141]
	v_lshl_add_u64 v[200:201], s[16:17], 0, v[142:143]
	global_load_dwordx4 v[140:143], v[140:141], off
	s_nop 0
	global_load_dwordx4 v[204:207], v[200:201], off
	s_waitcnt lgkmcnt(1)
	v_mfma_f32_32x32x16_f16 v[114:129], v[152:155], v[160:163], v[114:129]
	s_waitcnt lgkmcnt(0)
	v_mfma_f32_32x32x16_f16 v[98:113], v[152:155], v[164:167], v[98:113]
	v_mfma_f32_32x32x16_f16 v[82:97], v[144:147], v[160:163], v[82:97]
	v_mfma_f32_32x32x16_f16 v[66:81], v[144:147], v[164:167], v[66:81]
	v_mfma_f32_32x32x16_f16 v[50:65], v[148:151], v[160:163], v[50:65]
	v_mfma_f32_32x32x16_f16 v[34:49], v[148:151], v[164:167], v[34:49]
	v_mfma_f32_32x32x16_f16 v[18:33], v[156:159], v[160:163], v[18:33]
	ds_read_b128 v[144:147], v130 offset:33312
	ds_read_b128 v[148:151], v130 offset:35872
	ds_read_b128 v[152:155], v130 offset:30752
	ds_read_b128 v[160:163], v130 offset:38432
	ds_read_b128 v[208:211], v0 offset:51232
	ds_read_b128 v[212:215], v0 offset:53792
	v_mfma_f32_32x32x16_f16 v[2:17], v[156:159], v[164:167], v[2:17]
	s_waitcnt lgkmcnt(1)
	v_mfma_f32_32x32x16_f16 v[114:129], v[152:155], v[208:211], v[114:129]
	s_waitcnt lgkmcnt(0)
	v_mfma_f32_32x32x16_f16 v[98:113], v[152:155], v[212:215], v[98:113]
	v_mfma_f32_32x32x16_f16 v[82:97], v[144:147], v[208:211], v[82:97]
	v_mfma_f32_32x32x16_f16 v[66:81], v[144:147], v[212:215], v[66:81]
	v_mfma_f32_32x32x16_f16 v[50:65], v[148:151], v[208:211], v[50:65]
	v_mfma_f32_32x32x16_f16 v[34:49], v[148:151], v[212:215], v[34:49]
	v_mfma_f32_32x32x16_f16 v[18:33], v[160:163], v[208:211], v[18:33]
	v_mfma_f32_32x32x16_f16 v[2:17], v[160:163], v[212:215], v[2:17]
	s_waitcnt vmcnt(11)
	ds_write_b128 v202, v[172:175]
	s_waitcnt vmcnt(10)
	ds_write_b128 v202, v[176:179] offset:5120
	s_waitcnt vmcnt(9)
	ds_write_b128 v202, v[180:183] offset:10240
	s_waitcnt vmcnt(8)
	ds_write_b128 v202, v[184:187] offset:15360
	s_waitcnt vmcnt(7)
	ds_write_b128 v202, v[188:191] offset:20480
	s_waitcnt vmcnt(6)
	ds_write_b128 v202, v[192:195] offset:25600
	s_waitcnt lgkmcnt(0)
	s_barrier
	ds_read_b128 v[144:147], v130
	ds_read_b128 v[148:151], v130 offset:2560
	ds_read_b128 v[152:155], v130 offset:5120
	ds_read_b128 v[156:159], v130 offset:7680
	ds_read_b128 v[160:163], v0 offset:20480
	ds_read_b128 v[164:167], v0 offset:23040
	s_waitcnt lgkmcnt(1)
	v_mfma_f32_32x32x16_f16 v[114:129], v[144:147], v[160:163], v[114:129]
	s_waitcnt lgkmcnt(0)
	v_mfma_f32_32x32x16_f16 v[98:113], v[144:147], v[164:167], v[98:113]
	v_mfma_f32_32x32x16_f16 v[82:97], v[148:151], v[160:163], v[82:97]
	v_mfma_f32_32x32x16_f16 v[66:81], v[148:151], v[164:167], v[66:81]
	v_mfma_f32_32x32x16_f16 v[50:65], v[152:155], v[160:163], v[50:65]
	v_mfma_f32_32x32x16_f16 v[34:49], v[152:155], v[164:167], v[34:49]
	v_mfma_f32_32x32x16_f16 v[18:33], v[156:159], v[160:163], v[18:33]
	ds_read_b128 v[144:147], v130 offset:32
	ds_read_b128 v[148:151], v130 offset:2592
	ds_read_b128 v[152:155], v130 offset:5152
	ds_read_b128 v[160:163], v130 offset:7712
	ds_read_b128 v[172:175], v0 offset:20512
	ds_read_b128 v[176:179], v0 offset:23072
	v_mfma_f32_32x32x16_f16 v[2:17], v[156:159], v[164:167], v[2:17]
	s_waitcnt lgkmcnt(1)
	v_mfma_f32_32x32x16_f16 v[114:129], v[144:147], v[172:175], v[114:129]
	s_waitcnt lgkmcnt(0)
	v_mfma_f32_32x32x16_f16 v[98:113], v[144:147], v[176:179], v[98:113]
	v_mfma_f32_32x32x16_f16 v[82:97], v[148:151], v[172:175], v[82:97]
	v_mfma_f32_32x32x16_f16 v[66:81], v[148:151], v[176:179], v[66:81]
	v_mfma_f32_32x32x16_f16 v[50:65], v[152:155], v[172:175], v[50:65]
	v_mfma_f32_32x32x16_f16 v[34:49], v[152:155], v[176:179], v[34:49]
	v_mfma_f32_32x32x16_f16 v[18:33], v[160:163], v[172:175], v[18:33]
	v_mfma_f32_32x32x16_f16 v[2:17], v[160:163], v[176:179], v[2:17]
	s_waitcnt vmcnt(5)
	ds_write_b128 v202, v[168:171] offset:30720
	s_waitcnt vmcnt(4)
	ds_write_b128 v202, v[132:135] offset:35840
	s_waitcnt vmcnt(3)
	ds_write_b128 v202, v[196:199] offset:40960
	s_waitcnt vmcnt(2)
	ds_write_b128 v202, v[136:139] offset:46080
	s_waitcnt vmcnt(1)
	ds_write_b128 v202, v[140:143] offset:51200
	s_waitcnt vmcnt(0)
	ds_write_b128 v202, v[204:207] offset:56320
	s_waitcnt lgkmcnt(0)
	s_barrier
; DI void phase_uproj(const P& p, int l, char* smem, int boff, int geff) {
;     ...
;       epi_foreach_w(acc, m0, n0, [&](int rbase, int n, const f32x16& v) {
;         const int b = rbase < TL ? (rbase >> 12) : ((rbase - TL) >> 8);
;         const int srb = srow_of(rbase);
;         const int head = n >> 7, dd = n & 127;
;         if (dd < 64) {
;           h16* k = kn + ((size_t)(b * 7 + head) * SA) * 64 + dd;
; #pragma unroll
;           for (int i = 0; i < 16; ++i) k[(size_t)EROW(srb, i) * 64] = (h16)v[i];
;         } else {
;           const int s = srb - b * SA;
;           h16* vt = VmT + ((size_t)(b * 8 + head) * 64 + (dd - 64)) * SA + s;
; #pragma unroll
;           for (int g = 0; g < 4; ++g) {
;             h16x4 o; o.x = (h16)v[4 * g]; o.y = (h16)v[4 * g + 1]; o.z = (h16)v[4 * g + 2]; o.w = (h16)v[4 * g + 3];
;             *(h16x4*)(vt + 8 * g) = o;
;           }
	ds_read_b128 v[132:135], v130 offset:33280
	ds_read_b128 v[136:139], v130 offset:35840
	ds_read_b128 v[140:143], v130 offset:30720
	ds_read_b128 v[144:147], v130 offset:38400
	ds_read_b128 v[148:151], v0 offset:51200
	ds_read_b128 v[152:155], v0 offset:53760
	s_waitcnt lgkmcnt(1)
	v_mfma_f32_32x32x16_f16 v[114:129], v[140:143], v[148:151], v[114:129]
	s_waitcnt lgkmcnt(0)
	v_mfma_f32_32x32x16_f16 v[98:113], v[140:143], v[152:155], v[98:113]
	v_mfma_f32_32x32x16_f16 v[82:97], v[132:135], v[148:151], v[82:97]
	v_mfma_f32_32x32x16_f16 v[66:81], v[132:135], v[152:155], v[66:81]
	v_mfma_f32_32x32x16_f16 v[50:65], v[136:139], v[148:151], v[50:65]
	v_mfma_f32_32x32x16_f16 v[34:49], v[136:139], v[152:155], v[34:49]
	v_mfma_f32_32x32x16_f16 v[18:33], v[144:147], v[148:151], v[18:33]
	ds_read_b128 v[132:135], v130 offset:33312
	ds_read_b128 v[136:139], v130 offset:35872
	ds_read_b128 v[140:143], v130 offset:30752
	ds_read_b128 v[148:151], v130 offset:38432
	ds_read_b128 v[156:159], v0 offset:51232
	ds_read_b128 v[160:163], v0 offset:53792
	v_mfma_f32_32x32x16_f16 v[2:17], v[144:147], v[152:155], v[2:17]
	s_waitcnt lgkmcnt(1)
	v_mfma_f32_32x32x16_f16 v[114:129], v[140:143], v[156:159], v[114:129]
	s_waitcnt lgkmcnt(0)
	v_mfma_f32_32x32x16_f16 v[98:113], v[140:143], v[160:163], v[98:113]
	v_mfma_f32_32x32x16_f16 v[82:97], v[132:135], v[156:159], v[82:97]
	v_mfma_f32_32x32x16_f16 v[66:81], v[132:135], v[160:163], v[66:81]
	v_mfma_f32_32x32x16_f16 v[50:65], v[136:139], v[156:159], v[50:65]
	v_mfma_f32_32x32x16_f16 v[34:49], v[136:139], v[160:163], v[34:49]
	v_mfma_f32_32x32x16_f16 v[18:33], v[148:151], v[156:159], v[18:33]
	v_mfma_f32_32x32x16_f16 v[2:17], v[148:151], v[160:163], v[2:17]
	v_mov_b32_e32 v131, v203
	v_mov_b32_e32 v0, v203
	s_barrier
	s_nop 0
	v_and_b32_e32 v130, 0xffffff80, v0
	v_add_u32_e32 v130, s21, v130
	v_lshrrev_b32_e32 v132, 3, v131
	v_and_or_b32 v133, v132, 4, v130
	v_mov_b32_e32 v134, v133
	s_nop 0
	v_add_u32_e32 v130, 0xffff8000, v134
	v_cmp_gt_i32_e32 vcc, s87, v134
	v_cmp_lt_i32_e64 s[0:1], s33, v134
	v_lshrrev_b32_e32 v132, 8, v130
	s_and_saveexec_b64 s[26:27], s[0:1]
	s_xor_b64 s[0:1], exec, s[26:27]
	v_mul_u32_u24_e32 v130, 0x1100, v132
	s_movk_i32 s2, 0xff
	v_and_or_b32 v130, v134, s2, v130
	v_add_u32_e32 v130, 0x1000, v130
	s_or_saveexec_b64 s[0:1], s[0:1]
	v_ashrrev_i32_e32 v135, 12, v134
	s_xor_b64 exec, exec, s[0:1]
	v_and_b32_e32 v130, 0xfff, v134
	v_mad_i32_i24 v130, v135, s64, v130
	s_or_b64 exec, exec, s[0:1]
	v_and_b32_e32 v131, 31, v131
	v_and_or_b32 v134, v0, 64, v131
	v_and_b32_e32 v0, 64, v0
	v_cndmask_b32_e32 v131, v132, v135, vcc
	s_ashr_i32 s24, s24, 7
	v_cmp_ne_u32_e32 vcc, 0, v0
	v_subrev_u32_e32 v132, 64, v134
	s_and_saveexec_b64 s[0:1], vcc
	s_xor_b64 s[0:1], exec, s[0:1]
	s_cbranch_execz .LBB0_2123
	v_mad_u64_u32 v[136:137], s[26:27], v131, s68, v[130:131]
	v_lshl_add_u32 v130, v131, 3, s24
	v_ashrrev_i32_e32 v131, 31, v130
	v_lshlrev_b64 v[130:131], 6, v[130:131]
	v_or_b32_e32 v0, v130, v132
	v_mov_b64_e32 v[138:139], s[48:49]
	s_movk_i32 s2, 0x2200
	v_mad_u64_u32 v[138:139], s[26:27], v0, s2, v[138:139]
	v_mad_i32_i24 v139, v131, s2, v139
	v_ashrrev_i32_e32 v137, 31, v136
	v_lshl_add_u64 v[130:131], v[136:137], 1, v[138:139]
	v_bfe_u32 v138, v203, 5, 1
	v_lshlrev_b32_e32 v138, 3, v138
	v_mov_b32_e32 v139, 0
	v_lshl_add_u64 v[130:131], v[130:131], 0, v[138:139]
	v_cvt_pk_f16_f32 v117, v116, v117
	v_cvt_pk_f16_f32 v116, v114, v115
	v_cvt_pk_f16_f32 v115, v120, v121
	v_cvt_pk_f16_f32 v114, v118, v119
	global_store_dwordx2 v[130:131], v[114:115], off offset:8
	v_cvt_pk_f16_f32 v115, v124, v125
	v_cvt_pk_f16_f32 v114, v122, v123
	global_store_dwordx2 v[130:131], v[114:115], off offset:32
	v_cvt_pk_f16_f32 v115, v128, v129
	v_cvt_pk_f16_f32 v114, v126, v127
	global_store_dwordx2 v[130:131], v[116:117], off
	global_store_dwordx2 v[130:131], v[114:115], off offset:40

; DI void phase_uproj(const P& p, int l, char* smem, int boff, int geff) {
;     ...
;       epi_foreach_w(acc, m0, n0, [&](int rbase, int n, const f32x16& v) {
;         const int b = rbase < TL ? (rbase >> 12) : ((rbase - TL) >> 8);
;         const int srb = srow_of(rbase);
;         const int head = n >> 7, dd = n & 127;
;         if (dd < 64) {
;           h16* k = kn + ((size_t)(b * 7 + head) * SA) * 64 + dd;
; #pragma unroll
;           for (int i = 0; i < 16; ++i) k[(size_t)EROW(srb, i) * 64] = (h16)v[i];
;         } else {
;           const int s = srb - b * SA;
;           h16* vt = VmT + ((size_t)(b * 8 + head) * 64 + (dd - 64)) * SA + s;
; #pragma unroll
;           for (int g = 0; g < 4; ++g) {
;             h16x4 o; o.x = (h16)v[4 * g]; o.y = (h16)v[4 * g + 1]; o.z = (h16)v[4 * g + 2]; o.w = (h16)v[4 * g + 3];
;             *(h16x4*)(vt + 8 * g) = o;
;           }
.LBB0_2125:
	s_or_b64 exec, exec, s[0:1]
	v_mov_b32_e32 v116, v133
	s_nop 0
	v_add_u32_e32 v114, 0xffff8000, v116
	v_cmp_gt_i32_e64 s[0:1], s87, v116
	v_cmp_lt_i32_e64 s[38:39], s33, v116
	v_lshrrev_b32_e32 v115, 8, v114
	s_and_saveexec_b64 s[26:27], s[38:39]
	s_xor_b64 s[38:39], exec, s[26:27]
	v_mul_u32_u24_e32 v114, 0x1100, v115
	s_movk_i32 s2, 0xff
	v_and_or_b32 v114, v116, s2, v114
	v_add_u32_e32 v114, 0x1000, v114
	s_or_saveexec_b64 s[38:39], s[38:39]
	v_ashrrev_i32_e32 v117, 12, v116
	s_xor_b64 exec, exec, s[38:39]
	v_and_b32_e32 v114, 0xfff, v116
	v_mad_i32_i24 v114, v117, s64, v114
	s_or_b64 exec, exec, s[38:39]
	v_cndmask_b32_e64 v115, v115, v117, s[0:1]
	v_subrev_u32_e32 v116, 32, v134
	s_and_saveexec_b64 s[0:1], vcc
	s_xor_b64 s[0:1], exec, s[0:1]
	s_cbranch_execz .LBB0_2131
	v_mad_u64_u32 v[118:119], s[26:27], v115, s68, v[114:115]
	v_lshl_add_u32 v114, v115, 3, s24
	v_ashrrev_i32_e32 v115, 31, v114
	v_lshlrev_b64 v[114:115], 6, v[114:115]
	v_or_b32_e32 v114, v114, v116
	v_mov_b64_e32 v[120:121], s[48:49]
	s_movk_i32 s2, 0x2200
	v_mad_u64_u32 v[120:121], s[26:27], v114, s2, v[120:121]
	v_mad_i32_i24 v121, v115, s2, v121
	v_ashrrev_i32_e32 v119, 31, v118
	v_lshl_add_u64 v[114:115], v[118:119], 1, v[120:121]
	v_bfe_u32 v120, v203, 5, 1
	v_lshlrev_b32_e32 v120, 3, v120
	v_mov_b32_e32 v121, 0
	v_lshl_add_u64 v[114:115], v[114:115], 0, v[120:121]
	v_cvt_pk_f16_f32 v101, v100, v101
	v_cvt_pk_f16_f32 v100, v98, v99
	v_cvt_pk_f16_f32 v99, v104, v105
	v_cvt_pk_f16_f32 v98, v102, v103
	global_store_dwordx2 v[114:115], v[98:99], off offset:8
	v_cvt_pk_f16_f32 v99, v108, v109
	v_cvt_pk_f16_f32 v98, v106, v107
	global_store_dwordx2 v[114:115], v[98:99], off offset:32
	v_cvt_pk_f16_f32 v99, v112, v113
	v_cvt_pk_f16_f32 v98, v110, v111
	global_store_dwordx2 v[114:115], v[100:101], off
	global_store_dwordx2 v[114:115], v[98:99], off offset:40

; DI void phase_uproj(const P& p, int l, char* smem, int boff, int geff) {
;     ...
;       epi_foreach_w(acc, m0, n0, [&](int rbase, int n, const f32x16& v) {
;         const int b = rbase < TL ? (rbase >> 12) : ((rbase - TL) >> 8);
;         const int srb = srow_of(rbase);
;         const int head = n >> 7, dd = n & 127;
;         if (dd < 64) {
;           h16* k = kn + ((size_t)(b * 7 + head) * SA) * 64 + dd;
; #pragma unroll
;           for (int i = 0; i < 16; ++i) k[(size_t)EROW(srb, i) * 64] = (h16)v[i];
;         } else {
;           const int s = srb - b * SA;
;           h16* vt = VmT + ((size_t)(b * 8 + head) * 64 + (dd - 64)) * SA + s;
; #pragma unroll
;           for (int g = 0; g < 4; ++g) {
;             h16x4 o; o.x = (h16)v[4 * g]; o.y = (h16)v[4 * g + 1]; o.z = (h16)v[4 * g + 2]; o.w = (h16)v[4 * g + 3];
;             *(h16x4*)(vt + 8 * g) = o;
;           }
.LBB0_2133:
	s_or_b64 exec, exec, s[0:1]
	v_or_b32_e32 v100, 32, v133
	v_mov_b32_e32 v101, v100
	s_nop 0
	v_add_u32_e32 v98, 0xffff8000, v101
	v_cmp_gt_i32_e64 s[0:1], s87, v101
	v_cmp_lt_i32_e64 s[38:39], s33, v101
	v_lshrrev_b32_e32 v99, 8, v98
	s_and_saveexec_b64 s[26:27], s[38:39]
	s_xor_b64 s[38:39], exec, s[26:27]
	v_mul_u32_u24_e32 v98, 0x1100, v99
	s_movk_i32 s2, 0xff
	v_and_or_b32 v98, v101, s2, v98
	v_add_u32_e32 v98, 0x1000, v98
	s_or_saveexec_b64 s[38:39], s[38:39]
	v_ashrrev_i32_e32 v102, 12, v101
	s_xor_b64 exec, exec, s[38:39]
	v_and_b32_e32 v98, 0xfff, v101
	v_mad_i32_i24 v98, v102, s64, v98
	s_or_b64 exec, exec, s[38:39]
	v_cndmask_b32_e64 v99, v99, v102, s[0:1]
	s_and_saveexec_b64 s[0:1], vcc
	s_xor_b64 s[0:1], exec, s[0:1]
	s_cbranch_execz .LBB0_2139
	v_mad_u64_u32 v[102:103], s[26:27], v99, s68, v[98:99]
	v_lshl_add_u32 v98, v99, 3, s24
	v_ashrrev_i32_e32 v99, 31, v98
	v_lshlrev_b64 v[98:99], 6, v[98:99]
	v_or_b32_e32 v98, v98, v132
	v_mov_b64_e32 v[104:105], s[48:49]
	s_movk_i32 s2, 0x2200
	v_mad_u64_u32 v[104:105], s[26:27], v98, s2, v[104:105]
	v_mad_i32_i24 v105, v99, s2, v105
	v_ashrrev_i32_e32 v103, 31, v102
	v_lshl_add_u64 v[98:99], v[102:103], 1, v[104:105]
	v_bfe_u32 v104, v203, 5, 1
	v_lshlrev_b32_e32 v104, 3, v104
	v_mov_b32_e32 v105, 0
	v_lshl_add_u64 v[98:99], v[98:99], 0, v[104:105]
	v_cvt_pk_f16_f32 v85, v84, v85
	v_cvt_pk_f16_f32 v84, v82, v83
	v_cvt_pk_f16_f32 v83, v88, v89
	v_cvt_pk_f16_f32 v82, v86, v87
	global_store_dwordx2 v[98:99], v[82:83], off offset:8
	v_cvt_pk_f16_f32 v83, v92, v93
	v_cvt_pk_f16_f32 v82, v90, v91
	global_store_dwordx2 v[98:99], v[82:83], off offset:32
	v_cvt_pk_f16_f32 v83, v96, v97
	v_cvt_pk_f16_f32 v82, v94, v95
	global_store_dwordx2 v[98:99], v[84:85], off
	global_store_dwordx2 v[98:99], v[82:83], off offset:40

; DI void phase_uproj(const P& p, int l, char* smem, int boff, int geff) {
;     ...
;       epi_foreach_w(acc, m0, n0, [&](int rbase, int n, const f32x16& v) {
;         const int b = rbase < TL ? (rbase >> 12) : ((rbase - TL) >> 8);
;         const int srb = srow_of(rbase);
;         const int head = n >> 7, dd = n & 127;
;         if (dd < 64) {
;           h16* k = kn + ((size_t)(b * 7 + head) * SA) * 64 + dd;
; #pragma unroll
;           for (int i = 0; i < 16; ++i) k[(size_t)EROW(srb, i) * 64] = (h16)v[i];
;         } else {
;           const int s = srb - b * SA;
;           h16* vt = VmT + ((size_t)(b * 8 + head) * 64 + (dd - 64)) * SA + s;
; #pragma unroll
;           for (int g = 0; g < 4; ++g) {
;             h16x4 o; o.x = (h16)v[4 * g]; o.y = (h16)v[4 * g + 1]; o.z = (h16)v[4 * g + 2]; o.w = (h16)v[4 * g + 3];
;             *(h16x4*)(vt + 8 * g) = o;
;           }
.LBB0_2141:
	s_or_b64 exec, exec, s[0:1]
	s_nop 0
	v_add_u32_e32 v82, 0xffff8000, v100
	v_cmp_gt_i32_e64 s[0:1], s87, v100
	v_cmp_lt_i32_e64 s[38:39], s33, v100
	v_lshrrev_b32_e32 v83, 8, v82
	s_and_saveexec_b64 s[26:27], s[38:39]
	s_xor_b64 s[38:39], exec, s[26:27]
	v_mul_u32_u24_e32 v82, 0x1100, v83
	s_movk_i32 s2, 0xff
	v_and_or_b32 v82, v100, s2, v82
	v_add_u32_e32 v82, 0x1000, v82
	s_or_saveexec_b64 s[38:39], s[38:39]
	v_ashrrev_i32_e32 v84, 12, v100
	s_xor_b64 exec, exec, s[38:39]
	v_and_b32_e32 v82, 0xfff, v100
	v_mad_i32_i24 v82, v84, s64, v82
	s_or_b64 exec, exec, s[38:39]
	v_cndmask_b32_e64 v83, v83, v84, s[0:1]
	s_and_saveexec_b64 s[0:1], vcc
	s_xor_b64 s[0:1], exec, s[0:1]
	s_cbranch_execz .LBB0_2147
	v_mad_u64_u32 v[84:85], s[26:27], v83, s68, v[82:83]
	v_lshl_add_u32 v82, v83, 3, s24
	v_ashrrev_i32_e32 v83, 31, v82
	v_lshlrev_b64 v[82:83], 6, v[82:83]
	v_or_b32_e32 v82, v82, v116
	v_mov_b64_e32 v[86:87], s[48:49]
	s_movk_i32 s2, 0x2200
	v_mad_u64_u32 v[86:87], s[26:27], v82, s2, v[86:87]
	v_mad_i32_i24 v87, v83, s2, v87
	v_ashrrev_i32_e32 v85, 31, v84
	v_lshl_add_u64 v[82:83], v[84:85], 1, v[86:87]
	v_bfe_u32 v86, v203, 5, 1
	v_lshlrev_b32_e32 v86, 3, v86
	v_mov_b32_e32 v87, 0
	v_lshl_add_u64 v[82:83], v[82:83], 0, v[86:87]
	v_cvt_pk_f16_f32 v69, v68, v69
	v_cvt_pk_f16_f32 v68, v66, v67
	v_cvt_pk_f16_f32 v67, v72, v73
	v_cvt_pk_f16_f32 v66, v70, v71
	global_store_dwordx2 v[82:83], v[66:67], off offset:8
	v_cvt_pk_f16_f32 v67, v76, v77
	v_cvt_pk_f16_f32 v66, v74, v75
	global_store_dwordx2 v[82:83], v[66:67], off offset:32
	v_cvt_pk_f16_f32 v67, v80, v81
	v_cvt_pk_f16_f32 v66, v78, v79
	global_store_dwordx2 v[82:83], v[68:69], off
	global_store_dwordx2 v[82:83], v[66:67], off offset:40

; DI void phase_uproj(const P& p, int l, char* smem, int boff, int geff) {
;     ...
;       epi_foreach_w(acc, m0, n0, [&](int rbase, int n, const f32x16& v) {
;         const int b = rbase < TL ? (rbase >> 12) : ((rbase - TL) >> 8);
;         const int srb = srow_of(rbase);
;         const int head = n >> 7, dd = n & 127;
;         if (dd < 64) {
;           h16* k = kn + ((size_t)(b * 7 + head) * SA) * 64 + dd;
; #pragma unroll
;           for (int i = 0; i < 16; ++i) k[(size_t)EROW(srb, i) * 64] = (h16)v[i];
;         } else {
;           const int s = srb - b * SA;
;           h16* vt = VmT + ((size_t)(b * 8 + head) * 64 + (dd - 64)) * SA + s;
; #pragma unroll
;           for (int g = 0; g < 4; ++g) {
;             h16x4 o; o.x = (h16)v[4 * g]; o.y = (h16)v[4 * g + 1]; o.z = (h16)v[4 * g + 2]; o.w = (h16)v[4 * g + 3];
;             *(h16x4*)(vt + 8 * g) = o;
;           }
.LBB0_2149:
	s_or_b64 exec, exec, s[0:1]
	v_or_b32_e32 v68, 64, v133
	v_mov_b32_e32 v69, v68
	s_nop 0
	v_add_u32_e32 v66, 0xffff8000, v69
	v_cmp_gt_i32_e64 s[0:1], s87, v69
	v_cmp_lt_i32_e64 s[38:39], s33, v69
	v_lshrrev_b32_e32 v67, 8, v66
	s_and_saveexec_b64 s[26:27], s[38:39]
	s_xor_b64 s[38:39], exec, s[26:27]
	v_mul_u32_u24_e32 v66, 0x1100, v67
	s_movk_i32 s2, 0xff
	v_and_or_b32 v66, v69, s2, v66
	v_add_u32_e32 v66, 0x1000, v66
	s_or_saveexec_b64 s[38:39], s[38:39]
	v_ashrrev_i32_e32 v70, 12, v69
	s_xor_b64 exec, exec, s[38:39]
	v_and_b32_e32 v66, 0xfff, v69
	v_mad_i32_i24 v66, v70, s64, v66
	s_or_b64 exec, exec, s[38:39]
	v_cndmask_b32_e64 v67, v67, v70, s[0:1]
	s_and_saveexec_b64 s[0:1], vcc
	s_xor_b64 s[0:1], exec, s[0:1]
	s_cbranch_execz .LBB0_2155
	v_mad_u64_u32 v[70:71], s[26:27], v67, s68, v[66:67]
	v_lshl_add_u32 v66, v67, 3, s24
	v_ashrrev_i32_e32 v67, 31, v66
	v_lshlrev_b64 v[66:67], 6, v[66:67]
	v_or_b32_e32 v66, v66, v132
	v_mov_b64_e32 v[72:73], s[48:49]
	s_movk_i32 s2, 0x2200
	v_mad_u64_u32 v[72:73], s[26:27], v66, s2, v[72:73]
	v_mad_i32_i24 v73, v67, s2, v73
	v_ashrrev_i32_e32 v71, 31, v70
	v_lshl_add_u64 v[66:67], v[70:71], 1, v[72:73]
	v_bfe_u32 v72, v203, 5, 1
	v_lshlrev_b32_e32 v72, 3, v72
	v_mov_b32_e32 v73, 0
	v_lshl_add_u64 v[66:67], v[66:67], 0, v[72:73]
	v_cvt_pk_f16_f32 v53, v52, v53
	v_cvt_pk_f16_f32 v52, v50, v51
	v_cvt_pk_f16_f32 v51, v56, v57
	v_cvt_pk_f16_f32 v50, v54, v55
	global_store_dwordx2 v[66:67], v[50:51], off offset:8
	v_cvt_pk_f16_f32 v51, v60, v61
	v_cvt_pk_f16_f32 v50, v58, v59
	global_store_dwordx2 v[66:67], v[50:51], off offset:32
	v_cvt_pk_f16_f32 v51, v64, v65
	v_cvt_pk_f16_f32 v50, v62, v63
	global_store_dwordx2 v[66:67], v[52:53], off
	global_store_dwordx2 v[66:67], v[50:51], off offset:40

; DI void phase_uproj(const P& p, int l, char* smem, int boff, int geff) {
;     ...
;       epi_foreach_w(acc, m0, n0, [&](int rbase, int n, const f32x16& v) {
;         const int b = rbase < TL ? (rbase >> 12) : ((rbase - TL) >> 8);
;         const int srb = srow_of(rbase);
;         const int head = n >> 7, dd = n & 127;
;         if (dd < 64) {
;           h16* k = kn + ((size_t)(b * 7 + head) * SA) * 64 + dd;
; #pragma unroll
;           for (int i = 0; i < 16; ++i) k[(size_t)EROW(srb, i) * 64] = (h16)v[i];
;         } else {
;           const int s = srb - b * SA;
;           h16* vt = VmT + ((size_t)(b * 8 + head) * 64 + (dd - 64)) * SA + s;
; #pragma unroll
;           for (int g = 0; g < 4; ++g) {
;             h16x4 o; o.x = (h16)v[4 * g]; o.y = (h16)v[4 * g + 1]; o.z = (h16)v[4 * g + 2]; o.w = (h16)v[4 * g + 3];
;             *(h16x4*)(vt + 8 * g) = o;
;           }
.LBB0_2157:
	s_or_b64 exec, exec, s[0:1]
	s_nop 0
	v_add_u32_e32 v50, 0xffff8000, v68
	v_cmp_gt_i32_e64 s[0:1], s87, v68
	v_cmp_lt_i32_e64 s[38:39], s33, v68
	v_lshrrev_b32_e32 v51, 8, v50
	s_and_saveexec_b64 s[26:27], s[38:39]
	s_xor_b64 s[38:39], exec, s[26:27]
	v_mul_u32_u24_e32 v50, 0x1100, v51
	s_movk_i32 s2, 0xff
	v_and_or_b32 v50, v68, s2, v50
	v_add_u32_e32 v50, 0x1000, v50
	s_or_saveexec_b64 s[38:39], s[38:39]
	v_ashrrev_i32_e32 v52, 12, v68
	s_xor_b64 exec, exec, s[38:39]
	v_and_b32_e32 v50, 0xfff, v68
	v_mad_i32_i24 v50, v52, s64, v50
	s_or_b64 exec, exec, s[38:39]
	v_cndmask_b32_e64 v51, v51, v52, s[0:1]
	s_and_saveexec_b64 s[0:1], vcc
	s_xor_b64 s[0:1], exec, s[0:1]
	s_cbranch_execz .LBB0_2163
	v_mad_u64_u32 v[52:53], s[26:27], v51, s68, v[50:51]
	v_lshl_add_u32 v50, v51, 3, s24
	v_ashrrev_i32_e32 v51, 31, v50
	v_lshlrev_b64 v[50:51], 6, v[50:51]
	v_or_b32_e32 v50, v50, v116
	v_mov_b64_e32 v[54:55], s[48:49]
	s_movk_i32 s2, 0x2200
	v_mad_u64_u32 v[54:55], s[26:27], v50, s2, v[54:55]
	v_mad_i32_i24 v55, v51, s2, v55
	v_ashrrev_i32_e32 v53, 31, v52
	v_lshl_add_u64 v[50:51], v[52:53], 1, v[54:55]
	v_bfe_u32 v54, v203, 5, 1
	v_lshlrev_b32_e32 v54, 3, v54
	v_mov_b32_e32 v55, 0
	v_lshl_add_u64 v[50:51], v[50:51], 0, v[54:55]
	v_cvt_pk_f16_f32 v37, v36, v37
	v_cvt_pk_f16_f32 v36, v34, v35
	v_cvt_pk_f16_f32 v35, v40, v41
	v_cvt_pk_f16_f32 v34, v38, v39
	global_store_dwordx2 v[50:51], v[34:35], off offset:8
	v_cvt_pk_f16_f32 v35, v44, v45
	v_cvt_pk_f16_f32 v34, v42, v43
	global_store_dwordx2 v[50:51], v[34:35], off offset:32
	v_cvt_pk_f16_f32 v35, v48, v49
	v_cvt_pk_f16_f32 v34, v46, v47
	global_store_dwordx2 v[50:51], v[36:37], off
	global_store_dwordx2 v[50:51], v[34:35], off offset:40

; DI void phase_uproj(const P& p, int l, char* smem, int boff, int geff) {
;     ...
;       epi_foreach_w(acc, m0, n0, [&](int rbase, int n, const f32x16& v) {
;         const int b = rbase < TL ? (rbase >> 12) : ((rbase - TL) >> 8);
;         const int srb = srow_of(rbase);
;         const int head = n >> 7, dd = n & 127;
;         if (dd < 64) {
;           h16* k = kn + ((size_t)(b * 7 + head) * SA) * 64 + dd;
; #pragma unroll
;           for (int i = 0; i < 16; ++i) k[(size_t)EROW(srb, i) * 64] = (h16)v[i];
;         } else {
;           const int s = srb - b * SA;
;           h16* vt = VmT + ((size_t)(b * 8 + head) * 64 + (dd - 64)) * SA + s;
; #pragma unroll
;           for (int g = 0; g < 4; ++g) {
;             h16x4 o; o.x = (h16)v[4 * g]; o.y = (h16)v[4 * g + 1]; o.z = (h16)v[4 * g + 2]; o.w = (h16)v[4 * g + 3];
;             *(h16x4*)(vt + 8 * g) = o;
;           }
.LBB0_2165:
	s_or_b64 exec, exec, s[0:1]
	v_or_b32_e32 v36, 0x60, v133
	v_mov_b32_e32 v37, v36
	s_nop 0
	v_add_u32_e32 v34, 0xffff8000, v37
	v_cmp_gt_i32_e64 s[0:1], s87, v37
	v_cmp_lt_i32_e64 s[38:39], s33, v37
	v_lshrrev_b32_e32 v35, 8, v34
	s_and_saveexec_b64 s[26:27], s[38:39]
	s_xor_b64 s[38:39], exec, s[26:27]
	v_mul_u32_u24_e32 v34, 0x1100, v35
	s_movk_i32 s2, 0xff
	v_and_or_b32 v34, v37, s2, v34
	v_add_u32_e32 v34, 0x1000, v34
	s_or_saveexec_b64 s[38:39], s[38:39]
	v_ashrrev_i32_e32 v38, 12, v37
	s_xor_b64 exec, exec, s[38:39]
	v_and_b32_e32 v34, 0xfff, v37
	v_mad_i32_i24 v34, v38, s64, v34
	s_or_b64 exec, exec, s[38:39]
	v_cndmask_b32_e64 v35, v35, v38, s[0:1]
	s_and_saveexec_b64 s[0:1], vcc
	s_xor_b64 s[0:1], exec, s[0:1]
	s_cbranch_execz .LBB0_2171
	v_mad_u64_u32 v[38:39], s[26:27], v35, s68, v[34:35]
	v_lshl_add_u32 v34, v35, 3, s24
	v_ashrrev_i32_e32 v35, 31, v34
	v_lshlrev_b64 v[34:35], 6, v[34:35]
	v_or_b32_e32 v34, v34, v132
	v_mov_b64_e32 v[40:41], s[48:49]
	s_movk_i32 s2, 0x2200
	v_mad_u64_u32 v[40:41], s[26:27], v34, s2, v[40:41]
	v_mad_i32_i24 v41, v35, s2, v41
	v_ashrrev_i32_e32 v39, 31, v38
	v_lshl_add_u64 v[34:35], v[38:39], 1, v[40:41]
	v_bfe_u32 v40, v203, 5, 1
	v_lshlrev_b32_e32 v40, 3, v40
	v_mov_b32_e32 v41, 0
	v_lshl_add_u64 v[34:35], v[34:35], 0, v[40:41]
	v_cvt_pk_f16_f32 v21, v20, v21
	v_cvt_pk_f16_f32 v20, v18, v19
	v_cvt_pk_f16_f32 v19, v24, v25
	v_cvt_pk_f16_f32 v18, v22, v23
	global_store_dwordx2 v[34:35], v[18:19], off offset:8
	v_cvt_pk_f16_f32 v19, v28, v29
	v_cvt_pk_f16_f32 v18, v26, v27
	global_store_dwordx2 v[34:35], v[18:19], off offset:32
	v_cvt_pk_f16_f32 v19, v32, v33
	v_cvt_pk_f16_f32 v18, v30, v31
	global_store_dwordx2 v[34:35], v[20:21], off
	global_store_dwordx2 v[34:35], v[18:19], off offset:40

; DI void phase_uproj(const P& p, int l, char* smem, int boff, int geff) {
;     ...
;       epi_foreach_w(acc, m0, n0, [&](int rbase, int n, const f32x16& v) {
;         const int b = rbase < TL ? (rbase >> 12) : ((rbase - TL) >> 8);
;         const int srb = srow_of(rbase);
;         const int head = n >> 7, dd = n & 127;
;         if (dd < 64) {
;           h16* k = kn + ((size_t)(b * 7 + head) * SA) * 64 + dd;
; #pragma unroll
;           for (int i = 0; i < 16; ++i) k[(size_t)EROW(srb, i) * 64] = (h16)v[i];
;         } else {
;           const int s = srb - b * SA;
;           h16* vt = VmT + ((size_t)(b * 8 + head) * 64 + (dd - 64)) * SA + s;
; #pragma unroll
;           for (int g = 0; g < 4; ++g) {
;             h16x4 o; o.x = (h16)v[4 * g]; o.y = (h16)v[4 * g + 1]; o.z = (h16)v[4 * g + 2]; o.w = (h16)v[4 * g + 3];
;             *(h16x4*)(vt + 8 * g) = o;
;           }
.LBB0_2173:
	s_or_b64 exec, exec, s[0:1]
	s_nop 0
	v_add_u32_e32 v18, 0xffff8000, v36
	v_cmp_gt_i32_e64 s[0:1], s87, v36
	v_cmp_lt_i32_e64 s[38:39], s33, v36
	v_lshrrev_b32_e32 v19, 8, v18
	s_and_saveexec_b64 s[26:27], s[38:39]
	s_xor_b64 s[38:39], exec, s[26:27]
	v_mul_u32_u24_e32 v18, 0x1100, v19
	s_movk_i32 s2, 0xff
	v_and_or_b32 v18, v36, s2, v18
	v_add_u32_e32 v18, 0x1000, v18
	s_or_saveexec_b64 s[38:39], s[38:39]
	v_ashrrev_i32_e32 v20, 12, v36
	s_xor_b64 exec, exec, s[38:39]
	v_and_b32_e32 v18, 0xfff, v36
	v_mad_i32_i24 v18, v20, s64, v18
	s_or_b64 exec, exec, s[38:39]
	v_cndmask_b32_e64 v19, v19, v20, s[0:1]
	s_and_saveexec_b64 s[0:1], vcc
	s_xor_b64 s[0:1], exec, s[0:1]
	s_cbranch_execz .LBB0_2179
	v_mad_u64_u32 v[20:21], s[26:27], v19, s68, v[18:19]
	v_lshl_add_u32 v18, v19, 3, s24
	v_ashrrev_i32_e32 v19, 31, v18
	v_lshlrev_b64 v[18:19], 6, v[18:19]
	v_or_b32_e32 v0, v18, v116
	v_mov_b64_e32 v[22:23], s[48:49]
	s_movk_i32 s2, 0x2200
	v_mad_u64_u32 v[22:23], s[26:27], v0, s2, v[22:23]
	v_mad_i32_i24 v23, v19, s2, v23
	v_ashrrev_i32_e32 v21, 31, v20
	v_lshl_add_u64 v[18:19], v[20:21], 1, v[22:23]
	v_bfe_u32 v22, v203, 5, 1
	v_lshlrev_b32_e32 v22, 3, v22
	v_mov_b32_e32 v23, 0
	v_lshl_add_u64 v[18:19], v[18:19], 0, v[22:23]
	v_cvt_pk_f16_f32 v5, v4, v5
	v_cvt_pk_f16_f32 v4, v2, v3
	v_cvt_pk_f16_f32 v3, v8, v9
	v_cvt_pk_f16_f32 v2, v6, v7
	global_store_dwordx2 v[18:19], v[2:3], off offset:8
	v_cvt_pk_f16_f32 v3, v12, v13
	v_cvt_pk_f16_f32 v2, v10, v11
	global_store_dwordx2 v[18:19], v[2:3], off offset:32
	v_cvt_pk_f16_f32 v3, v16, v17
	v_cvt_pk_f16_f32 v2, v14, v15
	global_store_dwordx2 v[18:19], v[4:5], off
	global_store_dwordx2 v[18:19], v[2:3], off offset:40

; DI int TIDX() { int t = threadIdx.x; asm volatile("" : "+v"(t)); return t; }
; template <int DK, bool MLA>
; DI void attn_item(const h16* __restrict__ Q, const h16* __restrict__ Kp, const h16* __restrict__ Kr, const h16* __restrict__ Vt,
;                   int kbeg, int kend, h16* __restrict__ out, h16* sm) {
;     ...
;   const int tid = TIDX(), lane = tid & 63, w = tid >> 6, r = lane & 31, hh = lane >> 5;
;   h16x8 qf[DK / 16];
;   {
;     const h16* qr = Q + (size_t)(w * 32 + r) * DK + hh * 8;
; #pragma unroll
;     for (int ks = 0; ks < DK / 16; ++ks) qf[ks] = *(const h16x8*)(qr + ks * 16);
;   }
;   f32x16 ot[2];
; #pragma unroll
;   for (int i = 0; i < 16; ++i) { ot[0][i] = 0.f; ot[1][i] = 0.f; }
;   float m = -1000.f, lsum = 0.f;
;   u32x4 rkA[NCH], rvA[2], rkB[NCH], rvB[2];
;     ...
;   const int ntile = (kend - kbeg) >> 6;
;   ATT_GLOAD(rkA, rvA, kbeg)
;   ATT_GLOAD(rkB, rvB, kbeg + 64)
.LBB0_2732:
	s_and_b32 s53, s27, 7
	s_or_b32 s11, s53, s13
	s_mov_b64 s[8:9], -1
	s_andn2_b64 vcc, exec, s[6:7]
	s_mul_i32 s27, s11, 0x1100
	s_cbranch_vccz .LBB0_2744
	v_mov_b32_e32 v12, v203
	s_add_i32 s6, s27, s10
	s_mov_b32 s7, s37
	s_movk_i32 s2, 0xffe0
	v_ashrrev_i32_e32 v0, 1, v12
	s_lshl_b64 s[6:7], s[6:7], 7
	s_waitcnt vmcnt(4)
	v_bfi_b32 v144, s2, v0, v12
	s_add_u32 s8, s21, s6
	s_waitcnt vmcnt(2)
	v_ashrrev_i32_e32 v145, 31, v144
	s_addc_u32 s9, s22, s7
	v_bfe_u32 v13, v12, 5, 1
	v_lshlrev_b64 v[2:3], 7, v[144:145]
	v_lshl_add_u64 v[2:3], s[8:9], 0, v[2:3]
	v_lshlrev_b32_e32 v0, 4, v13
	s_lshr_b32 s6, s53, 2
	v_lshl_add_u64 v[2:3], v[2:3], 0, v[0:1]
	s_or_b32 s6, s6, s14
	global_load_dwordx4 v[80:83], v[2:3], off
	global_load_dwordx4 v[84:87], v[2:3], off offset:32
	global_load_dwordx4 v[88:91], v[2:3], off offset:64
	global_load_dwordx4 v[92:95], v[2:3], off offset:96
	v_ashrrev_i32_e32 v2, 31, v12
	s_mul_i32 s38, s6, 0x88000
	v_lshrrev_b32_e32 v2, 29, v2
	v_add_u32_e32 v10, 0x100, v12
	s_add_u32 s6, s23, s38
	v_add_u32_e32 v8, v12, v2
	v_ashrrev_i32_e32 v2, 31, v10
	s_addc_u32 s7, s24, 0
	v_lshrrev_b32_e32 v2, 29, v2
	s_add_u32 s38, s25, s38
	v_add_u32_e32 v4, v10, v2
	s_addc_u32 s39, s48, 0
	v_ashrrev_i32_e32 v15, 3, v4
	s_or_b32 s9, s26, 64
	v_and_b32_e32 v4, -8, v4
	v_ashrrev_i32_e32 v14, 3, v8
	v_add_u32_e32 v2, s9, v15
	v_sub_u32_e32 v16, v10, v4
	v_and_b32_e32 v8, -8, v8
	s_sub_i32 s8, 0x1100, s26
	v_ashrrev_i32_e32 v3, 31, v2
	v_lshlrev_b32_e32 v4, 3, v16
	v_add_u32_e32 v6, s9, v14
	v_sub_u32_e32 v17, v12, v8
	s_lshr_b32 s8, s8, 6
	v_lshlrev_b64 v[2:3], 7, v[2:3]
	v_ashrrev_i32_e32 v5, 31, v4
	v_ashrrev_i32_e32 v7, 31, v6
	v_lshlrev_b32_e32 v8, 3, v17
	s_lshl_b32 s9, s26, 1
	v_lshl_add_u64 v[2:3], s[6:7], 0, v[2:3]
	v_lshlrev_b64 v[4:5], 1, v[4:5]
	v_lshlrev_b64 v[6:7], 7, v[6:7]
	v_ashrrev_i32_e32 v9, 31, v8
	s_add_u32 s38, s38, s9
	v_lshl_add_u64 v[2:3], v[2:3], 0, v[4:5]
	v_lshl_add_u64 v[6:7], s[6:7], 0, v[6:7]
	v_lshlrev_b64 v[8:9], 1, v[8:9]
	s_addc_u32 s39, s39, 0
	v_lshl_add_u64 v[6:7], v[6:7], 0, v[8:9]
	global_load_dwordx4 v[96:99], v[2:3], off
	global_load_dwordx4 v[100:103], v[6:7], off
	v_ashrrev_i32_e32 v18, 3, v10
	v_mov_b64_e32 v[2:3], s[38:39]
	s_movk_i32 s2, 0x2200
	v_lshlrev_b32_e32 v10, 4, v12
	v_ashrrev_i32_e32 v19, 3, v12
	v_add_u32_e32 v130, s26, v15
	v_mad_i64_i32 v[6:7], s[40:41], v18, s2, v[2:3]
	v_and_b32_e32 v10, 0x70, v10
	v_mov_b32_e32 v11, v1
	v_mad_i64_i32 v[2:3], s[40:41], v19, s2, v[2:3]
	v_add_u32_e32 v128, s26, v14
	v_lshl_add_u64 v[134:135], v[2:3], 0, v[10:11]
	v_lshl_add_u64 v[2:3], s[38:39], 0, v[10:11]
	v_ashrrev_i32_e32 v131, 31, v130
	v_mad_i64_i32 v[136:137], s[38:39], v18, s2, v[2:3]
	v_mad_i64_i32 v[138:139], s[38:39], v19, s2, v[2:3]
	v_lshlrev_b64 v[2:3], 7, v[130:131]
	v_ashrrev_i32_e32 v129, 31, v128
	v_lshl_add_u64 v[132:133], v[6:7], 0, v[10:11]
	v_lshl_add_u64 v[2:3], s[6:7], 0, v[2:3]
	v_lshlrev_b64 v[6:7], 7, v[128:129]
	v_lshl_add_u64 v[2:3], v[2:3], 0, v[4:5]
	v_lshl_add_u64 v[6:7], s[6:7], 0, v[6:7]
	global_load_dwordx4 v[104:107], v[132:133], off offset:128
	global_load_dwordx4 v[108:111], v[134:135], off offset:128
	global_load_dwordx4 v[112:115], v[136:137], off
	global_load_dwordx4 v[116:119], v[138:139], off
	v_lshl_add_u64 v[6:7], v[6:7], 0, v[8:9]
	global_load_dwordx4 v[120:123], v[2:3], off
	global_load_dwordx4 v[124:127], v[6:7], off
	v_and_b32_e32 v2, 31, v12
	v_mul_lo_u32 v3, v14, s28
	v_mul_u32_u24_e32 v2, 0x48, v2
	v_lshl_add_u32 v129, v17, 4, v3
	v_mul_lo_u32 v3, v15, s28
	v_mad_u64_u32 v[140:141], s[38:39], v19, s28, v[10:11]
	v_mad_u64_u32 v[142:143], s[38:39], v18, s28, v[10:11]
	v_lshlrev_b32_e32 v2, 1, v2
	v_mov_b32_e32 v14, v1
	v_mov_b32_e32 v15, v1
	v_lshl_add_u32 v131, v16, 4, v3
	v_lshl_add_u64 v[148:149], s[6:7], 0, v[8:9]
	v_lshl_add_u64 v[150:151], s[6:7], 0, v[4:5]
	v_add_u32_e32 v141, v2, v0
	s_waitcnt vmcnt(13)
	v_lshlrev_b32_e32 v146, 2, v13
	v_lshl_add_u32 v143, v13, 4, v2
	v_mov_b32_e32 v0, v1
	v_mov_b32_e32 v2, v1
	v_mov_b32_e32 v3, v1
	v_mov_b32_e32 v4, v1
	v_mov_b32_e32 v5, v1
	v_mov_b32_e32 v6, v1
	v_mov_b32_e32 v7, v1
	v_mov_b32_e32 v8, v1
	v_mov_b32_e32 v9, v1
	v_mov_b32_e32 v10, v1
	v_mov_b32_e32 v12, v1
	v_mov_b32_e32 v13, v1
	v_mov_b64_e32 v[30:31], v[14:15]
	v_mov_b64_e32 v[46:47], v[14:15]
	s_mov_b32 s9, 3
	s_waitcnt vmcnt(12)
	v_mov_b32_e32 v147, 0xc47a0000
	v_mov_b32_e32 v153, 0
	s_movk_i32 s6, 0xc0
	v_mov_b64_e32 v[28:29], v[12:13]
	v_mov_b64_e32 v[26:27], v[10:11]
	v_mov_b64_e32 v[24:25], v[8:9]
	v_mov_b64_e32 v[22:23], v[6:7]
	v_mov_b64_e32 v[20:21], v[4:5]
	v_mov_b64_e32 v[18:19], v[2:3]
	v_mov_b64_e32 v[16:17], v[0:1]
	v_mov_b64_e32 v[44:45], v[12:13]
	v_mov_b64_e32 v[42:43], v[10:11]
	v_mov_b64_e32 v[40:41], v[8:9]
	v_mov_b64_e32 v[38:39], v[6:7]
	v_mov_b64_e32 v[36:37], v[4:5]
	v_mov_b64_e32 v[34:35], v[2:3]
	v_mov_b64_e32 v[32:33], v[0:1]
	s_branch .LBB0_2735
; #define MFMA(a, b, c) __builtin_amdgcn_mfma_f32_32x32x16_f16((a), (b), (c), 0, 0, 0)
; template <int DK, bool MLA>
; DI void attn_item(const h16* __restrict__ Q, const h16* __restrict__ Kp, const h16* __restrict__ Kr, const h16* __restrict__ Vt,
;                   int kbeg, int kend, h16* __restrict__ out, h16* sm) {
;     ...
;     float ps = 0.f;
; #pragma unroll
;     for (int i = 0; i < 16; ++i) {
;       st[0][i] = __builtin_amdgcn_exp2f(st[0][i]);
;       st[1][i] = __builtin_amdgcn_exp2f(st[1][i]);
;       ps += st[0][i] + st[1][i];
;     }
;     lsum += ps;
; #pragma unroll
;     for (int s4 = 0; s4 < 4; ++s4) {
;       const int kt2 = s4 >> 1, hf = s4 & 1;
;       h16x8 pb;
; #pragma unroll
;       for (int j = 0; j < 8; ++j) pb[j] = (h16)st[kt2][8 * hf + j];
;       const int kb = kt2 * 32 + 16 * hf;
; #pragma unroll
;       for (int dt = 0; dt < 2; ++dt) {
;         const h16* vp = vsm + (dt * 32 + r) * 72 + kb + 4 * hh;
;         h16x4 lo = *(const h16x4*)vp, hi = *(const h16x4*)(vp + 8);
;         h16x8 va = __builtin_shufflevector(lo, hi, 0, 1, 2, 3, 4, 5, 6, 7);
;         ot[dt] = MFMA(va, pb, ot[dt]);
;       }
;     }
.LBB0_2734:
	v_exp_f32_e32 v152, v64
	v_exp_f32_e32 v154, v48
	v_exp_f32_e32 v155, v65
	v_exp_f32_e32 v156, v49
	v_exp_f32_e32 v157, v66
	v_exp_f32_e32 v158, v50
	v_exp_f32_e32 v159, v67
	v_exp_f32_e32 v160, v51
	v_add_f32_e32 v2, v154, v152
	v_exp_f32_e32 v161, v68
	v_exp_f32_e32 v162, v52
	v_add_f32_e32 v2, 0, v2
	v_add_f32_e32 v3, v156, v155
	v_exp_f32_e32 v14, v69
	v_exp_f32_e32 v6, v53
	v_add_f32_e32 v2, v3, v2
	v_add_f32_e32 v3, v158, v157
	v_add_f32_e32 v2, v3, v2
	v_add_f32_e32 v3, v160, v159
	v_add_f32_e32 v15, v3, v2
	v_add_f32_e32 v7, v162, v161
	v_pk_add_f32 v[2:3], v[6:7], v[14:15]
	v_exp_f32_e32 v7, v70
	v_pk_add_f32 v[48:49], v[2:3], v[2:3] op_sel_hi:[0,1]
	v_exp_f32_e32 v15, v54
	v_exp_f32_e32 v48, v71
	v_exp_f32_e32 v12, v55
	v_exp_f32_e32 v70, v56
	v_add_f32_e32 v13, v15, v7
	v_exp_f32_e32 v62, v62
	v_pk_add_f32 v[2:3], v[12:13], v[48:49]
	v_exp_f32_e32 v13, v72
	v_pk_add_f32 v[64:65], v[2:3], v[2:3] op_sel_hi:[0,1]
	v_exp_f32_e32 v64, v73
	v_exp_f32_e32 v2, v57
	v_add_f32_e32 v3, v70, v13
	v_cvt_pk_f16_f32 v49, v157, v159
	v_cvt_pk_f16_f32 v15, v15, v12
	v_pk_add_f32 v[4:5], v[2:3], v[64:65]
	v_exp_f32_e32 v3, v74
	v_pk_add_f32 v[66:67], v[4:5], v[4:5] op_sel_hi:[0,1]
	v_exp_f32_e32 v65, v58
	v_exp_f32_e32 v66, v75
	v_exp_f32_e32 v4, v59
	v_cvt_pk_f16_f32 v12, v154, v156
	v_add_f32_e32 v5, v65, v3
	s_addk_i32 s6, 0x80
	v_pk_add_f32 v[8:9], v[4:5], v[66:67]
	v_exp_f32_e32 v5, v76
	v_pk_add_f32 v[68:69], v[8:9], v[8:9] op_sel_hi:[0,1]
	v_exp_f32_e32 v67, v60
	v_exp_f32_e32 v68, v77
	v_exp_f32_e32 v8, v61
	s_add_i32 s9, s9, 2
	v_add_f32_e32 v9, v67, v5
	s_cmp_lt_u32 s38, s8
	v_pk_add_f32 v[10:11], v[8:9], v[68:69]
	v_exp_f32_e32 v9, v78
	v_pk_add_f32 v[60:61], v[10:11], v[10:11] op_sel_hi:[0,1]
	v_exp_f32_e32 v60, v79
	v_exp_f32_e32 v10, v63
	v_add_f32_e32 v11, v62, v9
	v_pk_add_f32 v[50:51], v[10:11], v[60:61]
	s_nop 0
	v_add_f32_e32 v11, v50, v51
	v_add_f32_e32 v153, v0, v11
	v_add_u32_e32 v0, 0x6800, v143
	ds_read_b128 v[52:55], v0 offset:1024
	ds_read_b128 v[56:59], v0 offset:1056
	v_cvt_pk_f16_f32 v51, v7, v48
	v_cvt_pk_f16_f32 v50, v161, v14
	v_cvt_pk_f16_f32 v48, v152, v155
	v_add_u32_e32 v61, 0x7800, v143
	v_cvt_pk_f16_f32 v14, v162, v6
	s_waitcnt lgkmcnt(1)
	v_mfma_f32_32x32x16_f16 v[32:47], v[52:55], v[48:51], v[32:47]
	ds_read_b128 v[52:55], v61 offset:1536
	v_cvt_pk_f16_f32 v7, v62, v10
	v_cvt_pk_f16_f32 v6, v67, v8
	s_waitcnt lgkmcnt(0)
	v_mfma_f32_32x32x16_f16 v[16:31], v[52:55], v[48:51], v[16:31]
	ds_read_b128 v[52:55], v61 offset:1568
	v_cvt_pk_f16_f32 v51, v9, v60
	v_cvt_pk_f16_f32 v50, v5, v68
	v_cvt_pk_f16_f32 v49, v3, v66
	v_cvt_pk_f16_f32 v48, v13, v64
	v_cvt_pk_f16_f32 v13, v158, v160
	ds_read_b128 v[8:11], v0 offset:1120
	v_mfma_f32_32x32x16_f16 v[32:47], v[56:59], v[48:51], v[32:47]
	v_cvt_pk_f16_f32 v5, v65, v4
	v_cvt_pk_f16_f32 v4, v70, v2
	s_waitcnt lgkmcnt(1)
	v_mfma_f32_32x32x16_f16 v[16:31], v[52:55], v[48:51], v[16:31]
	ds_read_b128 v[48:51], v0 offset:1088
	s_waitcnt lgkmcnt(0)
	v_mfma_f32_32x32x16_f16 v[32:47], v[48:51], v[12:15], v[32:47]
	ds_read_b128 v[48:51], v61 offset:1600
	v_mfma_f32_32x32x16_f16 v[32:47], v[8:11], v[4:7], v[32:47]
	ds_read_b128 v[8:11], v61 offset:1632
	s_waitcnt lgkmcnt(1)
	v_mfma_f32_32x32x16_f16 v[16:31], v[48:51], v[12:15], v[16:31]
	s_waitcnt lgkmcnt(0)
	v_mfma_f32_32x32x16_f16 v[16:31], v[8:11], v[4:7], v[16:31]
	s_cbranch_scc0 .LBB0_2743

; #define MFMA(a, b, c) __builtin_amdgcn_mfma_f32_32x32x16_f16((a), (b), (c), 0, 0, 0)
; template <int DK, bool MLA>
; DI void attn_item(const h16* __restrict__ Q, const h16* __restrict__ Kp, const h16* __restrict__ Kr, const h16* __restrict__ Vt,
;                   int kbeg, int kend, h16* __restrict__ out, h16* sm) {
;     ...
; #pragma unroll
;     for (int i = 0; i < NCH; ++i) {
;       const int c = tid + 256 * i, key = c / NKC, part = c % NKC;
;       *(u32x4*)(ksm + key * KS + part * 8) = RK[i];
;     }
; #pragma unroll
;     for (int i = 0; i < 2; ++i) {
;       const int c = tid + 256 * i, dv = c >> 3, kc = c & 7;
;       *(u32x4*)(vsm + dv * 72 + kc * 8) = RV[i];
;     }
;     __syncthreads();
;     if (it + 2 < ntile) ATT_GLOAD(RK, RV, kbeg + (it + 2) * 64)
;     ...
;     float ps = 0.f;
; #pragma unroll
;     for (int i = 0; i < 16; ++i) {
;       st[0][i] = __builtin_amdgcn_exp2f(st[0][i]);
;       st[1][i] = __builtin_amdgcn_exp2f(st[1][i]);
;       ps += st[0][i] + st[1][i];
;     }
;     lsum += ps;
; #pragma unroll
;     for (int s4 = 0; s4 < 4; ++s4) {
;       const int kt2 = s4 >> 1, hf = s4 & 1;
;       h16x8 pb;
; #pragma unroll
;       for (int j = 0; j < 8; ++j) pb[j] = (h16)st[kt2][8 * hf + j];
;       const int kb = kt2 * 32 + 16 * hf;
; #pragma unroll
;       for (int dt = 0; dt < 2; ++dt) {
;         const h16* vp = vsm + (dt * 32 + r) * 72 + kb + 4 * hh;
;         h16x4 lo = *(const h16x4*)vp, hi = *(const h16x4*)(vp + 8);
;         h16x8 va = __builtin_shufflevector(lo, hi, 0, 1, 2, 3, 4, 5, 6, 7);
;         ot[dt] = MFMA(va, pb, ot[dt]);
;       }
;     }
.LBB0_2739:
	v_exp_f32_e32 v166, v64
	v_exp_f32_e32 v13, v65
	v_exp_f32_e32 v15, v66
	v_exp_f32_e32 v152, v67
	v_exp_f32_e32 v156, v68
	v_exp_f32_e32 v157, v69
	v_exp_f32_e32 v168, v70
	v_exp_f32_e32 v160, v71
	v_exp_f32_e32 v12, v60
	v_add_u32_e32 v60, 0x2000, v143
	v_exp_f32_e32 v158, v52
	v_exp_f32_e32 v159, v53
	v_exp_f32_e32 v169, v54
	v_exp_f32_e32 v163, v55
	v_exp_f32_e32 v164, v56
	v_exp_f32_e32 v165, v57
	v_exp_f32_e32 v10, v58
	v_exp_f32_e32 v11, v59
	ds_read_b128 v[52:55], v60 offset:1024
	ds_read_b128 v[56:59], v60 offset:1056
	v_exp_f32_e32 v167, v48
	v_exp_f32_e32 v14, v49
	v_exp_f32_e32 v154, v50
	v_exp_f32_e32 v155, v51
	v_exp_f32_e32 v4, v61
	v_cvt_pk_f16_f32 v51, v168, v160
	v_cvt_pk_f16_f32 v50, v156, v157
	v_cvt_pk_f16_f32 v49, v15, v152
	v_cvt_pk_f16_f32 v48, v166, v13
	v_add_u32_e32 v61, 0x3000, v143
	v_exp_f32_e32 v161, v72
	s_waitcnt lgkmcnt(1)
	v_mfma_f32_32x32x16_f16 v[32:47], v[52:55], v[48:51], v[32:47]
	ds_read_b128 v[52:55], v61 offset:1536
	v_exp_f32_e32 v162, v73
	v_exp_f32_e32 v7, v74
	v_exp_f32_e32 v8, v75
	v_exp_f32_e32 v9, v76
	v_exp_f32_e32 v0, v77
	v_exp_f32_e32 v2, v78
	s_waitcnt lgkmcnt(0)
	v_mfma_f32_32x32x16_f16 v[16:31], v[52:55], v[48:51], v[16:31]
	ds_read_b128 v[52:55], v61 offset:1568
	v_exp_f32_e32 v3, v79
	v_cvt_pk_f16_f32 v50, v9, v0
	v_cvt_pk_f16_f32 v49, v7, v8
	v_cvt_pk_f16_f32 v48, v161, v162
	v_cvt_pk_f16_f32 v51, v2, v3
	v_exp_f32_e32 v5, v62
	v_exp_f32_e32 v6, v63
	s_waitcnt lgkmcnt(0)
	v_mfma_f32_32x32x16_f16 v[16:31], v[52:55], v[48:51], v[16:31]
	ds_read_b128 v[52:55], v60 offset:1088
	s_cmp_ge_u32 s9, s8
	v_mfma_f32_32x32x16_f16 v[32:47], v[56:59], v[48:51], v[32:47]
	v_cvt_pk_f16_f32 v51, v169, v163
	v_cvt_pk_f16_f32 v50, v158, v159
	v_cvt_pk_f16_f32 v49, v154, v155
	v_cvt_pk_f16_f32 v48, v167, v14
	s_waitcnt lgkmcnt(0)
	s_nop 0
	v_mfma_f32_32x32x16_f16 v[32:47], v[52:55], v[48:51], v[32:47]
	ds_read_b128 v[52:55], v61 offset:1600
	s_waitcnt lgkmcnt(0)
	v_mfma_f32_32x32x16_f16 v[16:31], v[52:55], v[48:51], v[16:31]
	ds_read_b128 v[52:55], v60 offset:1120
	v_cvt_pk_f16_f32 v51, v5, v6
	v_cvt_pk_f16_f32 v50, v12, v4
	v_cvt_pk_f16_f32 v49, v10, v11
	v_cvt_pk_f16_f32 v48, v164, v165
	s_waitcnt lgkmcnt(0)
	s_nop 0
	v_mfma_f32_32x32x16_f16 v[32:47], v[52:55], v[48:51], v[32:47]
	ds_read_b128 v[52:55], v61 offset:1632
	ds_write_b128 v129, v[100:103] offset:18432
	ds_write_b128 v131, v[96:99] offset:18432
	ds_write_b128 v140, v[108:111] offset:27648
	ds_write_b128 v142, v[104:107] offset:27648
	s_waitcnt lgkmcnt(0)
	s_barrier
	v_mfma_f32_32x32x16_f16 v[16:31], v[52:55], v[48:51], v[16:31]
	s_cbranch_scc1 .LBB0_2741
	v_add_u32_e32 v48, s6, v128
	v_ashrrev_i32_e32 v49, 31, v48
	v_add_u32_e32 v50, s6, v130
	v_lshlrev_b64 v[48:49], 7, v[48:49]
	v_ashrrev_i32_e32 v51, 31, v50
	s_ashr_i32 s7, s6, 31
	v_lshl_add_u64 v[48:49], v[148:149], 0, v[48:49]
	v_lshlrev_b64 v[50:51], 7, v[50:51]
	s_lshl_b64 s[40:41], s[6:7], 1
	v_lshl_add_u64 v[50:51], v[150:151], 0, v[50:51]
	global_load_dwordx4 v[100:103], v[48:49], off
	global_load_dwordx4 v[96:99], v[50:51], off
	v_lshl_add_u64 v[48:49], v[134:135], 0, s[40:41]
	v_lshl_add_u64 v[50:51], v[132:133], 0, s[40:41]
	global_load_dwordx4 v[108:111], v[48:49], off
	global_load_dwordx4 v[104:107], v[50:51], off

; DI int TIDX() { int t = threadIdx.x; asm volatile("" : "+v"(t)); return t; }
; template <int DK, bool MLA>
; DI void attn_item(const h16* __restrict__ Q, const h16* __restrict__ Kp, const h16* __restrict__ Kr, const h16* __restrict__ Vt,
;                   int kbeg, int kend, h16* __restrict__ out, h16* sm) {
;     ...
;   const int tid = TIDX(), lane = tid & 63, w = tid >> 6, r = lane & 31, hh = lane >> 5;
;   h16x8 qf[DK / 16];
;   {
;     const h16* qr = Q + (size_t)(w * 32 + r) * DK + hh * 8;
; #pragma unroll
;     for (int ks = 0; ks < DK / 16; ++ks) qf[ks] = *(const h16x8*)(qr + ks * 16);
;   }
;   f32x16 ot[2];
; #pragma unroll
;   for (int i = 0; i < 16; ++i) { ot[0][i] = 0.f; ot[1][i] = 0.f; }
;   float m = -1000.f, lsum = 0.f;
;   u32x4 rkA[NCH], rvA[2], rkB[NCH], rvB[2];
;     ...
;   const int ntile = (kend - kbeg) >> 6;
;   ATT_GLOAD(rkA, rvA, kbeg)
;   ATT_GLOAD(rkB, rvB, kbeg + 64)
.LBB0_2744:
	s_and_b64 vcc, exec, s[8:9]
	s_cbranch_vccz .LBB0_2721
	s_add_u32 s6, s27, s10
	s_addc_u32 s7, 0, 0
	s_mulk_i32 s7, 0xc0
	s_mul_hi_u32 s8, s6, 0xc0
	s_add_i32 s8, s8, s7
	s_mulk_i32 s6, 0xc0
	s_add_u32 s6, s15, s6
	v_mov_b32_e32 v17, v203
	s_addc_u32 s7, s16, s8
	s_movk_i32 s2, 0xffe0
	v_ashrrev_i32_e32 v0, 1, v17
	v_bfe_u32 v16, v17, 5, 1
	s_waitcnt vmcnt(4)
	v_bfi_b32 v144, s2, v0, v17
	v_mov_b64_e32 v[2:3], s[6:7]
	v_mad_i64_i32 v[2:3], s[6:7], v144, s29, v[2:3]
	v_lshlrev_b32_e32 v0, 4, v16
	v_lshl_add_u64 v[2:3], v[2:3], 0, v[0:1]
	global_load_dwordx4 v[80:83], v[2:3], off
	global_load_dwordx4 v[84:87], v[2:3], off offset:32
	global_load_dwordx4 v[88:91], v[2:3], off offset:64
	global_load_dwordx4 v[92:95], v[2:3], off offset:96
	global_load_dwordx4 v[96:99], v[2:3], off offset:128
	global_load_dwordx4 v[100:103], v[2:3], off offset:160
	s_mov_b32 s2, 0x2aaaaaab
	v_mul_hi_i32 v0, v17, s2
	v_lshrrev_b32_e32 v2, 31, v0
	v_ashrrev_i32_e32 v0, 1, v0
	v_add_u32_e32 v18, v0, v2
	s_mul_i32 s10, s11, 0x88000
	v_mul_lo_u32 v0, v18, 12
	s_add_u32 s6, s17, s10
	v_sub_u32_e32 v0, v17, v0
	v_add_u32_e32 v148, s26, v18
	s_addc_u32 s7, s18, 0
	v_cmp_gt_i32_e64 s[38:39], 8, v0
	v_cmp_lt_i32_e32 vcc, 7, v0
	v_ashrrev_i32_e32 v149, 31, v148
	v_lshlrev_b32_e32 v2, 3, v0
	s_and_saveexec_b64 s[8:9], vcc
	s_xor_b64 s[8:9], exec, s[8:9]
	v_lshlrev_b64 v[4:5], 6, v[148:149]
	v_lshl_add_u64 v[4:5], s[4:5], 0, v[4:5]
	v_mov_b32_e32 v3, v1
	v_lshl_add_u64 v[4:5], v[2:3], 1, v[4:5]
	v_lshl_add_u64 v[4:5], v[4:5], 0, s[74:75]
	s_or_saveexec_b64 s[8:9], s[8:9]
	v_ashrrev_i32_e32 v3, 31, v2
	s_xor_b64 exec, exec, s[8:9]
	v_lshlrev_b64 v[4:5], 7, v[148:149]
	v_lshl_add_u64 v[4:5], s[6:7], 0, v[4:5]
	v_lshl_add_u64 v[4:5], v[2:3], 1, v[4:5]
	s_or_b64 exec, exec, s[8:9]
	global_load_dwordx4 v[104:107], v[4:5], off
	v_add_u32_e32 v10, 0x100, v17
	v_mul_hi_i32 v0, v10, s2
	v_lshrrev_b32_e32 v4, 31, v0
	v_ashrrev_i32_e32 v0, 1, v0
	v_add_u32_e32 v19, v0, v4
	v_mul_lo_u32 v0, v19, 12
	v_sub_u32_e32 v0, v10, v0
	s_waitcnt vmcnt(10)
	v_add_u32_e32 v150, s26, v19
	v_cmp_gt_i32_e64 s[40:41], 8, v0
	v_cmp_lt_i32_e64 s[44:45], 7, v0
	v_ashrrev_i32_e32 v151, 31, v150
	v_lshlrev_b32_e32 v4, 3, v0
	s_and_saveexec_b64 s[8:9], s[44:45]
	s_xor_b64 s[8:9], exec, s[8:9]
	v_lshlrev_b64 v[6:7], 6, v[150:151]
	v_lshl_add_u64 v[6:7], s[4:5], 0, v[6:7]
	v_mov_b32_e32 v5, v1
	v_lshl_add_u64 v[6:7], v[4:5], 1, v[6:7]
	v_lshl_add_u64 v[6:7], v[6:7], 0, s[74:75]
	s_or_saveexec_b64 s[8:9], s[8:9]
	v_ashrrev_i32_e32 v5, 31, v4
	s_xor_b64 exec, exec, s[8:9]
	v_lshlrev_b64 v[6:7], 7, v[150:151]
	v_lshl_add_u64 v[6:7], s[6:7], 0, v[6:7]
	v_lshl_add_u64 v[6:7], v[4:5], 1, v[6:7]
	s_or_b64 exec, exec, s[8:9]
	global_load_dwordx4 v[108:111], v[6:7], off
	v_add_u32_e32 v0, 0x200, v17
	v_mul_hi_i32 v6, v0, s2
	v_lshrrev_b32_e32 v7, 31, v6
	v_ashrrev_i32_e32 v6, 1, v6
	v_add_u32_e32 v20, v6, v7
	v_mul_lo_u32 v6, v20, 12
	v_sub_u32_e32 v0, v0, v6
	v_add_u32_e32 v152, s26, v20
	v_cmp_gt_i32_e64 s[42:43], 8, v0
	v_cmp_lt_i32_e64 s[46:47], 7, v0
	v_ashrrev_i32_e32 v153, 31, v152
	v_lshlrev_b32_e32 v0, 3, v0
	s_and_saveexec_b64 s[8:9], s[46:47]
	s_xor_b64 s[8:9], exec, s[8:9]
	v_lshlrev_b64 v[6:7], 6, v[152:153]
	v_lshl_add_u64 v[6:7], s[4:5], 0, v[6:7]
	v_lshl_add_u64 v[6:7], v[0:1], 1, v[6:7]
	v_lshl_add_u64 v[6:7], v[6:7], 0, s[74:75]
	s_or_saveexec_b64 s[8:9], s[8:9]
	v_ashrrev_i32_e32 v9, 31, v0
	s_xor_b64 exec, exec, s[8:9]
	v_lshlrev_b64 v[6:7], 7, v[152:153]
	v_lshl_add_u64 v[6:7], s[6:7], 0, v[6:7]
	v_mov_b32_e32 v8, v0
	v_lshl_add_u64 v[6:7], v[8:9], 1, v[6:7]
	s_or_b64 exec, exec, s[8:9]
	s_add_u32 s8, s19, s10
	s_addc_u32 s9, s20, 0
	global_load_dwordx4 v[112:115], v[6:7], off
	s_lshl_b32 s10, s26, 1
	v_lshlrev_b32_e32 v6, 3, v17
	s_add_u32 s8, s8, s10
	v_and_b32_e32 v6, 56, v6
	s_addc_u32 s9, s9, 0
	v_lshlrev_b32_e32 v6, 1, v6
	v_mov_b32_e32 v7, v1
	v_lshl_add_u64 v[12:13], s[8:9], 0, v[6:7]
	v_ashrrev_i32_e32 v21, 3, v17
	s_movk_i32 s2, 0x2200
	v_mad_i64_i32 v[154:155], s[10:11], v21, s2, v[12:13]
	v_ashrrev_i32_e32 v22, 3, v10
	v_mad_i64_i32 v[156:157], s[10:11], v22, s2, v[12:13]
	global_load_dwordx4 v[116:119], v[154:155], off
	global_load_dwordx4 v[120:123], v[156:157], off
	s_or_b32 s27, s26, 64
	v_add_u32_e32 v12, s27, v18
	v_ashrrev_i32_e32 v13, 31, v12
	s_and_saveexec_b64 s[10:11], vcc
	s_xor_b64 s[10:11], exec, s[10:11]
	v_lshlrev_b64 v[10:11], 6, v[12:13]
	v_lshl_add_u64 v[10:11], s[4:5], 0, v[10:11]
	v_mov_b32_e32 v12, v2
	v_mov_b32_e32 v13, v1
	v_lshl_add_u64 v[10:11], v[12:13], 1, v[10:11]
	v_lshl_add_u64 v[10:11], v[10:11], 0, s[74:75]
	s_andn2_saveexec_b64 s[10:11], s[10:11]
	v_lshlrev_b64 v[10:11], 7, v[12:13]
	v_lshl_add_u64 v[10:11], s[6:7], 0, v[10:11]
	v_lshl_add_u64 v[10:11], v[2:3], 1, v[10:11]
	s_or_b64 exec, exec, s[10:11]
	global_load_dwordx4 v[124:127], v[10:11], off
	v_add_u32_e32 v12, s27, v19
	v_ashrrev_i32_e32 v13, 31, v12
	s_and_saveexec_b64 s[10:11], s[44:45]
	s_xor_b64 s[10:11], exec, s[10:11]
	v_lshlrev_b64 v[10:11], 6, v[12:13]
	v_lshl_add_u64 v[10:11], s[4:5], 0, v[10:11]
	v_mov_b32_e32 v12, v4
	v_mov_b32_e32 v13, v1
	v_lshl_add_u64 v[10:11], v[12:13], 1, v[10:11]
	v_lshl_add_u64 v[10:11], v[10:11], 0, s[74:75]
	s_andn2_saveexec_b64 s[10:11], s[10:11]
	v_lshlrev_b64 v[10:11], 7, v[12:13]
	v_lshl_add_u64 v[10:11], s[6:7], 0, v[10:11]
	v_lshl_add_u64 v[10:11], v[4:5], 1, v[10:11]
	s_or_b64 exec, exec, s[10:11]
	global_load_dwordx4 v[128:131], v[10:11], off
	v_add_u32_e32 v14, s27, v20
	v_ashrrev_i32_e32 v15, 31, v14
	s_and_saveexec_b64 s[10:11], s[46:47]
	s_xor_b64 s[10:11], exec, s[10:11]
	v_lshlrev_b64 v[8:9], 6, v[14:15]
	v_lshl_add_u64 v[8:9], s[4:5], 0, v[8:9]
	v_lshl_add_u64 v[8:9], v[0:1], 1, v[8:9]
	v_lshl_add_u64 v[12:13], v[8:9], 0, s[74:75]
	s_or_saveexec_b64 s[10:11], s[10:11]
	v_mov_b64_e32 v[10:11], v[0:1]
	s_xor_b64 exec, exec, s[10:11]
	v_lshlrev_b64 v[10:11], 7, v[14:15]
	v_lshl_add_u64 v[10:11], s[6:7], 0, v[10:11]
	v_mov_b32_e32 v8, v0
	v_lshl_add_u64 v[12:13], v[8:9], 1, v[10:11]
	v_mov_b64_e32 v[10:11], v[8:9]
	s_or_b64 exec, exec, s[10:11]
	v_mad_i64_i32 v[14:15], s[10:11], v22, s2, 0
	v_mad_i64_i32 v[8:9], s[10:11], v21, s2, 0
	global_load_dwordx4 v[132:135], v[12:13], off
	v_lshl_add_u64 v[12:13], s[8:9], 0, v[14:15]
	v_mov_b32_e32 v7, v1
	s_waitcnt vmcnt(16)
; #define MFMA(a, b, c) __builtin_amdgcn_mfma_f32_32x32x16_f16((a), (b), (c), 0, 0, 0)
; DI int TIDX() { int t = threadIdx.x; asm volatile("" : "+v"(t)); return t; }
; template <int DK, bool MLA>
; DI void attn_item(const h16* __restrict__ Q, const h16* __restrict__ Kp, const h16* __restrict__ Kr, const h16* __restrict__ Vt,
;                   int kbeg, int kend, h16* __restrict__ out, h16* sm) {
;     ...
;   const int tid = TIDX(), lane = tid & 63, w = tid >> 6, r = lane & 31, hh = lane >> 5;
;   h16x8 qf[DK / 16];
;   {
;     const h16* qr = Q + (size_t)(w * 32 + r) * DK + hh * 8;
; #pragma unroll
;     for (int ks = 0; ks < DK / 16; ++ks) qf[ks] = *(const h16x8*)(qr + ks * 16);
;   }
;   f32x16 ot[2];
; #pragma unroll
;   for (int i = 0; i < 16; ++i) { ot[0][i] = 0.f; ot[1][i] = 0.f; }
;   float m = -1000.f, lsum = 0.f;
;   u32x4 rkA[NCH], rvA[2], rkB[NCH], rvB[2];
;     ...
;   const int ntile = (kend - kbeg) >> 6;
;   ATT_GLOAD(rkA, rvA, kbeg)
;   ATT_GLOAD(rkB, rvB, kbeg + 64)
;     ...
;     float ps = 0.f;
; #pragma unroll
;     for (int i = 0; i < 16; ++i) {
;       st[0][i] = __builtin_amdgcn_exp2f(st[0][i]);
;       st[1][i] = __builtin_amdgcn_exp2f(st[1][i]);
;       ps += st[0][i] + st[1][i];
;     }
;     lsum += ps;
; #pragma unroll
;     for (int s4 = 0; s4 < 4; ++s4) {
;       const int kt2 = s4 >> 1, hf = s4 & 1;
;       h16x8 pb;
; #pragma unroll
;       for (int j = 0; j < 8; ++j) pb[j] = (h16)st[kt2][8 * hf + j];
;       const int kb = kt2 * 32 + 16 * hf;
; #pragma unroll
;       for (int dt = 0; dt < 2; ++dt) {
;         const h16* vp = vsm + (dt * 32 + r) * 72 + kb + 4 * hh;
;         h16x4 lo = *(const h16x4*)vp, hi = *(const h16x4*)(vp + 8);
;         h16x8 va = __builtin_shufflevector(lo, hi, 0, 1, 2, 3, 4, 5, 6, 7);
;         ot[dt] = MFMA(va, pb, ot[dt]);
;       }
;     }
	v_lshl_add_u64 v[158:159], v[12:13], 0, v[6:7]
	v_lshl_add_u64 v[8:9], s[8:9], 0, v[8:9]
	v_lshl_add_u64 v[160:161], v[8:9], 0, v[6:7]
	global_load_dwordx4 v[136:139], v[158:159], off offset:128
	global_load_dwordx4 v[140:143], v[160:161], off offset:128
	s_movk_i32 s2, 0xd0
	v_mul_lo_u32 v7, v18, s2
	s_waitcnt vmcnt(16)
	v_lshl_add_u32 v147, v2, 1, v7
	v_mul_lo_u32 v7, v19, s2
	v_and_b32_e32 v8, 31, v17
	v_lshl_add_u32 v149, v4, 1, v7
	v_mul_lo_u32 v7, v20, s2
	v_lshl_add_u32 v151, v0, 1, v7
	v_lshl_add_u64 v[174:175], v[0:1], 1, s[4:5]
	v_mul_u32_u24_e32 v0, 0x68, v8
	v_lshlrev_b32_e32 v9, 3, v16
	v_mad_u64_u32 v[162:163], s[10:11], v21, s28, v[6:7]
	v_lshlrev_b32_e32 v0, 1, v0
	v_mad_u64_u32 v[164:165], s[10:11], v22, s28, v[6:7]
	v_mov_b32_e32 v6, v2
	v_mov_b32_e32 v7, v1
	v_lshl_add_u64 v[168:169], v[2:3], 1, s[6:7]
	v_mov_b32_e32 v2, v4
	v_mov_b32_e32 v3, v1
	v_lshl_add_u32 v163, v9, 1, v0
	v_mul_u32_u24_e32 v0, 0x48, v8
	v_mov_b32_e32 v14, v1
	v_mov_b32_e32 v15, v1
	s_sub_i32 s8, 0x1100, s26
	v_lshl_add_u64 v[166:167], v[6:7], 1, s[4:5]
	v_lshl_add_u64 v[170:171], v[2:3], 1, s[4:5]
	v_lshl_add_u64 v[172:173], v[4:5], 1, s[6:7]
	v_lshl_add_u64 v[176:177], v[10:11], 1, s[6:7]
	v_lshlrev_b32_e32 v146, 2, v16
	v_lshlrev_b32_e32 v165, 1, v9
	v_lshl_add_u32 v165, v0, 1, v165
	v_mov_b32_e32 v0, v1
	v_mov_b32_e32 v2, v1
	v_mov_b32_e32 v4, v1
	v_mov_b32_e32 v5, v1
	v_mov_b32_e32 v6, v1
	v_mov_b32_e32 v8, v1
	v_mov_b32_e32 v9, v1
	v_mov_b32_e32 v10, v1
	v_mov_b32_e32 v11, v1
	v_mov_b32_e32 v12, v1
	v_mov_b32_e32 v13, v1
	v_mov_b64_e32 v[30:31], v[14:15]
	v_mov_b64_e32 v[46:47], v[14:15]
	v_ashrrev_i32_e32 v145, 31, v144
	s_lshr_b32 s8, s8, 6
	s_mov_b32 s9, 3
	v_mov_b32_e32 v178, 0xc47a0000
	v_mov_b32_e32 v153, 0
	s_movk_i32 s6, 0xc0
	v_mov_b64_e32 v[28:29], v[12:13]
	v_mov_b64_e32 v[26:27], v[10:11]
	v_mov_b64_e32 v[24:25], v[8:9]
	v_mov_b64_e32 v[22:23], v[6:7]
	v_mov_b64_e32 v[20:21], v[4:5]
	v_mov_b64_e32 v[18:19], v[2:3]
	v_mov_b64_e32 v[16:17], v[0:1]
	v_mov_b64_e32 v[44:45], v[12:13]
	v_mov_b64_e32 v[42:43], v[10:11]
	v_mov_b64_e32 v[40:41], v[8:9]
	v_mov_b64_e32 v[38:39], v[6:7]
	v_mov_b64_e32 v[36:37], v[4:5]
	v_mov_b64_e32 v[34:35], v[2:3]
	v_mov_b64_e32 v[32:33], v[0:1]
	s_branch .LBB0_2771
.LBB0_2770:
	v_exp_f32_e32 v179, v64
	v_exp_f32_e32 v180, v48
	v_exp_f32_e32 v181, v65
	v_exp_f32_e32 v182, v49
	v_exp_f32_e32 v183, v66
	v_exp_f32_e32 v184, v50
	v_exp_f32_e32 v185, v67
	v_exp_f32_e32 v186, v51
	v_add_f32_e32 v2, v180, v179
	v_exp_f32_e32 v187, v68
	v_exp_f32_e32 v188, v52
	v_add_f32_e32 v2, 0, v2
	v_add_f32_e32 v3, v182, v181
	v_exp_f32_e32 v14, v69
	v_exp_f32_e32 v6, v53
	v_add_f32_e32 v2, v3, v2
	v_add_f32_e32 v3, v184, v183
	v_add_f32_e32 v2, v3, v2
	v_add_f32_e32 v3, v186, v185
	v_add_f32_e32 v15, v3, v2
	v_add_f32_e32 v7, v188, v187
	v_pk_add_f32 v[2:3], v[6:7], v[14:15]
	v_exp_f32_e32 v7, v70
	v_pk_add_f32 v[48:49], v[2:3], v[2:3] op_sel_hi:[0,1]
	v_exp_f32_e32 v15, v54
	v_exp_f32_e32 v48, v71
	v_exp_f32_e32 v12, v55
	v_exp_f32_e32 v70, v56
	v_add_f32_e32 v13, v15, v7
	v_exp_f32_e32 v62, v62
	v_pk_add_f32 v[2:3], v[12:13], v[48:49]
	v_exp_f32_e32 v13, v72
	v_pk_add_f32 v[64:65], v[2:3], v[2:3] op_sel_hi:[0,1]
	v_exp_f32_e32 v64, v73
	v_exp_f32_e32 v2, v57
	v_add_f32_e32 v3, v70, v13
	v_cvt_pk_f16_f32 v49, v183, v185
	v_cvt_pk_f16_f32 v15, v15, v12
	v_pk_add_f32 v[4:5], v[2:3], v[64:65]
	v_exp_f32_e32 v3, v74
	v_pk_add_f32 v[66:67], v[4:5], v[4:5] op_sel_hi:[0,1]
	v_exp_f32_e32 v65, v58
	v_exp_f32_e32 v66, v75
	v_exp_f32_e32 v4, v59
	v_cvt_pk_f16_f32 v12, v180, v182
	v_add_f32_e32 v5, v65, v3
	s_addk_i32 s6, 0x80
	v_pk_add_f32 v[8:9], v[4:5], v[66:67]
	v_exp_f32_e32 v5, v76
	v_pk_add_f32 v[68:69], v[8:9], v[8:9] op_sel_hi:[0,1]
	v_exp_f32_e32 v67, v60
	v_exp_f32_e32 v68, v77
	v_exp_f32_e32 v8, v61
	s_add_i32 s9, s9, 2
	v_add_f32_e32 v9, v67, v5
	s_cmp_lt_u32 s10, s8
	v_pk_add_f32 v[10:11], v[8:9], v[68:69]
	v_exp_f32_e32 v9, v78
	v_pk_add_f32 v[60:61], v[10:11], v[10:11] op_sel_hi:[0,1]
	v_exp_f32_e32 v60, v79
	v_exp_f32_e32 v10, v63
	v_add_f32_e32 v11, v62, v9
	v_pk_add_f32 v[50:51], v[10:11], v[60:61]
	s_nop 0
	v_add_f32_e32 v11, v50, v51
	v_add_f32_e32 v153, v0, v11
	v_add_u32_e32 v0, 0x8800, v165
	ds_read_b128 v[52:55], v0 offset:1024
	ds_read_b128 v[56:59], v0 offset:1056
	v_cvt_pk_f16_f32 v51, v7, v48
	v_cvt_pk_f16_f32 v50, v187, v14
	v_cvt_pk_f16_f32 v48, v179, v181
	v_add_u32_e32 v61, 0x9800, v165
	v_cvt_pk_f16_f32 v14, v188, v6
	s_waitcnt lgkmcnt(1)
	v_mfma_f32_32x32x16_f16 v[32:47], v[52:55], v[48:51], v[32:47]
	ds_read_b128 v[52:55], v61 offset:1536
	v_cvt_pk_f16_f32 v7, v62, v10
	v_cvt_pk_f16_f32 v6, v67, v8
	s_waitcnt lgkmcnt(0)
	v_mfma_f32_32x32x16_f16 v[16:31], v[52:55], v[48:51], v[16:31]
	ds_read_b128 v[52:55], v61 offset:1568
	v_cvt_pk_f16_f32 v51, v9, v60
	v_cvt_pk_f16_f32 v50, v5, v68
	v_cvt_pk_f16_f32 v49, v3, v66
	v_cvt_pk_f16_f32 v48, v13, v64
	v_cvt_pk_f16_f32 v13, v184, v186
	ds_read_b128 v[8:11], v0 offset:1120
	v_mfma_f32_32x32x16_f16 v[32:47], v[56:59], v[48:51], v[32:47]
	v_cvt_pk_f16_f32 v5, v65, v4
	v_cvt_pk_f16_f32 v4, v70, v2
	s_waitcnt lgkmcnt(1)
	v_mfma_f32_32x32x16_f16 v[16:31], v[52:55], v[48:51], v[16:31]
	ds_read_b128 v[48:51], v0 offset:1088
	s_waitcnt lgkmcnt(0)
	v_mfma_f32_32x32x16_f16 v[32:47], v[48:51], v[12:15], v[32:47]
	ds_read_b128 v[48:51], v61 offset:1600
	v_mfma_f32_32x32x16_f16 v[32:47], v[8:11], v[4:7], v[32:47]
	ds_read_b128 v[8:11], v61 offset:1632
	s_waitcnt lgkmcnt(1)
	v_mfma_f32_32x32x16_f16 v[16:31], v[48:51], v[12:15], v[16:31]
	s_waitcnt lgkmcnt(0)
	v_mfma_f32_32x32x16_f16 v[16:31], v[8:11], v[4:7], v[16:31]
	s_cbranch_scc0 .LBB0_2720

; #define MFMA(a, b, c) __builtin_amdgcn_mfma_f32_32x32x16_f16((a), (b), (c), 0, 0, 0)
; template <int DK, bool MLA>
; DI void attn_item(const h16* __restrict__ Q, const h16* __restrict__ Kp, const h16* __restrict__ Kr, const h16* __restrict__ Vt,
;                   int kbeg, int kend, h16* __restrict__ out, h16* sm) {
;     ...
; #pragma unroll
;     for (int i = 0; i < NCH; ++i) {
;       const int c = tid + 256 * i, key = c / NKC, part = c % NKC;
;       *(u32x4*)(ksm + key * KS + part * 8) = RK[i];
;     }
; #pragma unroll
;     for (int i = 0; i < 2; ++i) {
;       const int c = tid + 256 * i, dv = c >> 3, kc = c & 7;
;       *(u32x4*)(vsm + dv * 72 + kc * 8) = RV[i];
;     }
;     __syncthreads();
;     if (it + 2 < ntile) ATT_GLOAD(RK, RV, kbeg + (it + 2) * 64)
;     ...
;     float ps = 0.f;
; #pragma unroll
;     for (int i = 0; i < 16; ++i) {
;       st[0][i] = __builtin_amdgcn_exp2f(st[0][i]);
;       st[1][i] = __builtin_amdgcn_exp2f(st[1][i]);
;       ps += st[0][i] + st[1][i];
;     }
;     lsum += ps;
; #pragma unroll
;     for (int s4 = 0; s4 < 4; ++s4) {
;       const int kt2 = s4 >> 1, hf = s4 & 1;
;       h16x8 pb;
; #pragma unroll
;       for (int j = 0; j < 8; ++j) pb[j] = (h16)st[kt2][8 * hf + j];
;       const int kb = kt2 * 32 + 16 * hf;
; #pragma unroll
;       for (int dt = 0; dt < 2; ++dt) {
;         const h16* vp = vsm + (dt * 32 + r) * 72 + kb + 4 * hh;
;         h16x4 lo = *(const h16x4*)vp, hi = *(const h16x4*)(vp + 8);
;         h16x8 va = __builtin_shufflevector(lo, hi, 0, 1, 2, 3, 4, 5, 6, 7);
;         ot[dt] = MFMA(va, pb, ot[dt]);
;       }
;     }
.LBB0_2775:
	v_exp_f32_e32 v192, v64
	v_exp_f32_e32 v193, v65
	v_exp_f32_e32 v5, v66
	v_exp_f32_e32 v6, v67
	v_exp_f32_e32 v186, v68
	v_exp_f32_e32 v9, v69
	v_exp_f32_e32 v188, v70
	v_exp_f32_e32 v189, v71
	v_exp_f32_e32 v15, v60
	v_add_u32_e32 v60, 0x3000, v165
	v_exp_f32_e32 v187, v52
	v_exp_f32_e32 v13, v53
	v_exp_f32_e32 v190, v54
	v_exp_f32_e32 v191, v55
	v_exp_f32_e32 v183, v56
	v_exp_f32_e32 v184, v57
	v_exp_f32_e32 v185, v58
	v_exp_f32_e32 v14, v59
	ds_read_b128 v[52:55], v60 offset:1024
	ds_read_b128 v[56:59], v60 offset:1056
	v_exp_f32_e32 v194, v48
	v_exp_f32_e32 v195, v49
	v_exp_f32_e32 v7, v50
	v_exp_f32_e32 v8, v51
	v_exp_f32_e32 v179, v61
	v_cvt_pk_f16_f32 v51, v188, v189
	v_cvt_pk_f16_f32 v50, v186, v9
	v_cvt_pk_f16_f32 v49, v5, v6
	v_cvt_pk_f16_f32 v48, v192, v193
	v_add_u32_e32 v61, 0x4000, v165
	v_exp_f32_e32 v180, v72
	s_waitcnt lgkmcnt(1)
	v_mfma_f32_32x32x16_f16 v[32:47], v[52:55], v[48:51], v[32:47]
	ds_read_b128 v[52:55], v61 offset:1536
	v_exp_f32_e32 v181, v73
	v_exp_f32_e32 v182, v74
	v_exp_f32_e32 v10, v75
	v_exp_f32_e32 v11, v76
	v_exp_f32_e32 v12, v77
	v_exp_f32_e32 v0, v78
	s_waitcnt lgkmcnt(0)
	v_mfma_f32_32x32x16_f16 v[16:31], v[52:55], v[48:51], v[16:31]
	ds_read_b128 v[52:55], v61 offset:1568
	v_exp_f32_e32 v2, v79
	v_cvt_pk_f16_f32 v50, v11, v12
	v_cvt_pk_f16_f32 v49, v182, v10
	v_cvt_pk_f16_f32 v48, v180, v181
	v_cvt_pk_f16_f32 v51, v0, v2
	v_exp_f32_e32 v3, v62
	v_exp_f32_e32 v4, v63
	s_waitcnt lgkmcnt(0)
	v_mfma_f32_32x32x16_f16 v[16:31], v[52:55], v[48:51], v[16:31]
	ds_read_b128 v[52:55], v60 offset:1088
	s_cmp_ge_u32 s9, s8
	v_mfma_f32_32x32x16_f16 v[32:47], v[56:59], v[48:51], v[32:47]
	v_cvt_pk_f16_f32 v51, v190, v191
	v_cvt_pk_f16_f32 v50, v187, v13
	v_cvt_pk_f16_f32 v49, v7, v8
	v_cvt_pk_f16_f32 v48, v194, v195
	s_waitcnt lgkmcnt(0)
	s_nop 0
	v_mfma_f32_32x32x16_f16 v[32:47], v[52:55], v[48:51], v[32:47]
	ds_read_b128 v[52:55], v61 offset:1600
	s_waitcnt lgkmcnt(0)
	v_mfma_f32_32x32x16_f16 v[16:31], v[52:55], v[48:51], v[16:31]
	ds_read_b128 v[52:55], v60 offset:1120
	v_cvt_pk_f16_f32 v51, v3, v4
	v_cvt_pk_f16_f32 v50, v15, v179
	v_cvt_pk_f16_f32 v49, v185, v14
	v_cvt_pk_f16_f32 v48, v183, v184
	s_waitcnt lgkmcnt(0)
	s_nop 0
	v_mfma_f32_32x32x16_f16 v[32:47], v[52:55], v[48:51], v[32:47]
	ds_read_b128 v[52:55], v61 offset:1632
	s_waitcnt vmcnt(4)
	ds_write_b128 v147, v[124:127] offset:22528
	s_waitcnt vmcnt(3)
	ds_write_b128 v149, v[128:131] offset:22528
	s_waitcnt vmcnt(2)
	ds_write_b128 v151, v[132:135] offset:22528
	s_waitcnt vmcnt(0)
	ds_write_b128 v162, v[140:143] offset:35840
	ds_write_b128 v164, v[136:139] offset:35840
	s_waitcnt lgkmcnt(0)
	s_barrier
	v_mfma_f32_32x32x16_f16 v[16:31], v[52:55], v[48:51], v[16:31]
	s_cbranch_scc1 .LBB0_2777
	v_add_u32_e32 v48, s6, v148
	v_ashrrev_i32_e32 v49, 31, v48
	v_lshlrev_b64 v[50:51], 7, v[48:49]
	v_lshlrev_b64 v[48:49], 6, v[48:49]
	v_lshl_add_u64 v[48:49], v[166:167], 0, v[48:49]
	v_lshl_add_u64 v[50:51], v[168:169], 0, v[50:51]
	v_lshl_add_u64 v[48:49], v[48:49], 0, s[74:75]
	v_cndmask_b32_e64 v49, v49, v51, s[38:39]
	v_cndmask_b32_e64 v48, v48, v50, s[38:39]
	global_load_dwordx4 v[124:127], v[48:49], off
	v_add_u32_e32 v48, s6, v150
	v_ashrrev_i32_e32 v49, 31, v48
	v_lshlrev_b64 v[50:51], 7, v[48:49]
	v_lshlrev_b64 v[48:49], 6, v[48:49]
	v_lshl_add_u64 v[48:49], v[170:171], 0, v[48:49]
	v_lshl_add_u64 v[50:51], v[172:173], 0, v[50:51]
	v_lshl_add_u64 v[48:49], v[48:49], 0, s[74:75]
	v_cndmask_b32_e64 v49, v49, v51, s[40:41]
	v_cndmask_b32_e64 v48, v48, v50, s[40:41]
	global_load_dwordx4 v[128:131], v[48:49], off
	v_add_u32_e32 v48, s6, v152
	v_ashrrev_i32_e32 v49, 31, v48
	v_lshlrev_b64 v[50:51], 7, v[48:49]
	v_lshlrev_b64 v[48:49], 6, v[48:49]
	v_lshl_add_u64 v[48:49], v[174:175], 0, v[48:49]
	v_lshl_add_u64 v[50:51], v[176:177], 0, v[50:51]
	v_lshl_add_u64 v[48:49], v[48:49], 0, s[74:75]
	s_ashr_i32 s7, s6, 31
	v_cndmask_b32_e64 v49, v49, v51, s[42:43]
	v_cndmask_b32_e64 v48, v48, v50, s[42:43]
	s_lshl_b64 s[26:27], s[6:7], 1
	global_load_dwordx4 v[132:135], v[48:49], off
	v_lshl_add_u64 v[48:49], v[154:155], 0, s[26:27]
	v_lshl_add_u64 v[50:51], v[156:157], 0, s[26:27]
	global_load_dwordx4 v[140:143], v[48:49], off
	global_load_dwordx4 v[136:139], v[50:51], off
